# v32_align
# speedup vs baseline: 1.0068x; 1.0068x over previous
; DEVI f32x4 ozero() { float z = 0.f; asm volatile("" : "+v"(z)); return f32x4{z, z, z, z}; }
; #define WAIT_V(n) asm volatile("s_waitcnt vmcnt(" #n ")" ::: "memory")
; #define BAR __builtin_amdgcn_s_barrier()
; template <int EPI> ...
;     ...
;   const int brow = m0, bcol = n0;
;   const int wid = __builtin_amdgcn_readfirstlane(tid >> 6), lane = tid & 63, wr = wid >> 2, wc = wid & 3, fr = lane & 15, fq = lane >> 4;
;   f32x4 acc[2][2][4][2];
;   {
;     const f32x4 zq = ozero();
; #pragma unroll
;     for (int a_ = 0; a_ < 2; ++a_)
; #pragma unroll
;       for (int b_ = 0; b_ < 2; ++b_)
; #pragma unroll
;         for (int m = 0; m < 4; ++m) { acc[a_][b_][m][0] = zq; acc[a_][b_][m][1] = zq; }
;   }
;   bf16x8 At[4][2], B0[2][2], B1[2][2];
;   const int nt = K / BK;
;     ...
;   if (first) {
;     WAIT_V(0);
;     ISSUE_PRO(brow, bcol);
;   }
;   if (wr == 1) BAR;
;   WAIT_V(10); BAR;
;   WAIT_V(6); BAR;
;   for (int t = 0; t < nt - 2; t += 2) {
.LBB0_140:
	v_and_b32_e32 v132, 15, v134
	v_and_b32_e32 v1, 48, v134
	v_lshlrev_b32_e32 v2, 6, v132
	v_lshlrev_b32_e32 v4, 2, v134
	v_or_b32_e32 v3, v2, v1
	v_and_b32_e32 v4, 32, v4
	s_mov_b32 s14, 0x10000
	v_bitop3_b32 v5, v3, s14, v4 bitop3:0xde
	s_mov_b32 s14, 0x14000
	s_ashr_i32 s7, s34, 6
	v_bitop3_b32 v6, v3, s14, v4 bitop3:0xde
	s_mov_b32 s14, 0x18000
	v_lshlrev_b32_e32 v8, 6, v134
	s_and_b32 s35, s7, 3
	s_waitcnt vmcnt(10)
	s_barrier
	s_waitcnt vmcnt(6)
	s_lshl_b32 s44, s16, 6
	v_bitop3_b32 v7, v3, s14, v4 bitop3:0xde
	s_mov_b32 s14, 0x1c000
	s_lshl_b32 s16, s16, 13
	v_and_b32_e32 v8, 0x3c0, v8
	s_lshl_b32 s17, s35, 12
	v_bitop3_b32 v2, v2, v4, v1 bitop3:0x36
	v_bitop3_b32 v3, v3, s14, v4 bitop3:0xde
	v_bitop3_b32 v1, v8, v4, v1 bitop3:0x36
	s_or_b32 s18, s16, 0x800
	s_or_b32 s19, s16, 0x1000
	s_or_b32 s63, s16, 0x1800
	s_mov_b32 s62, -2
	s_mov_b64 s[14:15], 0
	v_add_u32_e32 v159, s17, v5
	v_add_u32_e32 v138, s16, v2
	v_add_u32_e32 v137, s18, v1
	v_add_u32_e32 v136, s19, v1
	v_add_u32_e32 v135, s63, v1
	v_add_u32_e32 v158, 0xc000, v133
	v_add_u32_e32 v157, 0xe000, v133
	v_add_u32_e32 v155, s17, v6
	v_add_u32_e32 v143, s17, v7
	v_add_u32_e32 v140, s17, v3
	v_mov_b32_e32 v1, v0
	v_mov_b32_e32 v2, v0
	v_mov_b32_e32 v3, v0
	v_mov_b32_e32 v4, v0
	v_mov_b32_e32 v5, v0
	v_mov_b32_e32 v6, v0
	v_mov_b32_e32 v7, v0
	v_mov_b32_e32 v8, v0
	v_mov_b32_e32 v9, v0
	v_mov_b32_e32 v10, v0
	v_mov_b32_e32 v11, v0
	v_mov_b32_e32 v12, v0
	v_mov_b32_e32 v13, v0
	v_mov_b32_e32 v14, v0
	v_mov_b32_e32 v15, v0
	v_mov_b32_e32 v16, v0
	v_mov_b32_e32 v17, v0
	v_mov_b32_e32 v18, v0
	v_mov_b32_e32 v19, v0
	v_mov_b32_e32 v20, v0
	v_mov_b32_e32 v21, v0
	v_mov_b32_e32 v22, v0
	v_mov_b32_e32 v23, v0
	v_mov_b32_e32 v24, v0
	v_mov_b32_e32 v25, v0
	v_mov_b32_e32 v26, v0
	v_mov_b32_e32 v27, v0
	v_mov_b32_e32 v28, v0
	v_mov_b32_e32 v29, v0
	v_mov_b32_e32 v30, v0
	v_mov_b32_e32 v31, v0
	v_mov_b32_e32 v32, v0
	v_mov_b32_e32 v33, v0
	v_mov_b32_e32 v34, v0
	v_mov_b32_e32 v35, v0
	v_mov_b32_e32 v36, v0
	v_mov_b32_e32 v37, v0
	v_mov_b32_e32 v38, v0
	v_mov_b32_e32 v39, v0
	v_mov_b32_e32 v40, v0
	v_mov_b32_e32 v41, v0
	v_mov_b32_e32 v42, v0
	v_mov_b32_e32 v43, v0
	v_mov_b32_e32 v44, v0
	v_mov_b32_e32 v45, v0
	v_mov_b32_e32 v46, v0
	v_mov_b32_e32 v47, v0
	v_mov_b32_e32 v48, v0
	v_mov_b32_e32 v49, v0
	v_mov_b32_e32 v50, v0
	v_mov_b32_e32 v51, v0
	v_mov_b32_e32 v52, v0
	v_mov_b32_e32 v53, v0
	v_mov_b32_e32 v54, v0
	v_mov_b32_e32 v55, v0
	v_mov_b32_e32 v56, v0
	v_mov_b32_e32 v57, v0
	v_mov_b32_e32 v58, v0
	v_mov_b32_e32 v59, v0
	v_mov_b32_e32 v60, v0
	v_mov_b32_e32 v61, v0
	v_mov_b32_e32 v62, v0
	v_mov_b32_e32 v63, v0
	v_mov_b32_e32 v64, v0
	v_mov_b32_e32 v65, v0
	v_mov_b32_e32 v66, v0
	v_mov_b32_e32 v67, v0
	v_mov_b32_e32 v68, v0
	v_mov_b32_e32 v69, v0
	v_mov_b32_e32 v70, v0
	v_mov_b32_e32 v71, v0
	v_mov_b32_e32 v72, v0
	v_mov_b32_e32 v73, v0
	v_mov_b32_e32 v74, v0
	v_mov_b32_e32 v75, v0
	v_mov_b32_e32 v76, v0
	v_mov_b32_e32 v77, v0
	v_mov_b32_e32 v78, v0
	v_mov_b32_e32 v79, v0
	v_mov_b32_e32 v80, v0
	v_mov_b32_e32 v81, v0
	v_mov_b32_e32 v82, v0
	v_mov_b32_e32 v83, v0
	v_mov_b32_e32 v84, v0
	v_mov_b32_e32 v85, v0
	v_mov_b32_e32 v86, v0
	v_mov_b32_e32 v87, v0
	v_mov_b32_e32 v88, v0
	v_mov_b32_e32 v89, v0
	v_mov_b32_e32 v90, v0
	v_mov_b32_e32 v91, v0
	v_mov_b32_e32 v92, v0
	v_mov_b32_e32 v93, v0
	v_mov_b32_e32 v94, v0
	v_mov_b32_e32 v95, v0
	v_mov_b32_e32 v96, v0
	v_mov_b32_e32 v97, v0
	v_mov_b32_e32 v98, v0
	v_mov_b32_e32 v99, v0
	v_mov_b32_e32 v100, v0
	v_mov_b32_e32 v101, v0
	v_mov_b32_e32 v102, v0
	v_mov_b32_e32 v103, v0
	v_mov_b32_e32 v104, v0
	v_mov_b32_e32 v105, v0
	v_mov_b32_e32 v106, v0
	v_mov_b32_e32 v107, v0
	v_mov_b32_e32 v108, v0
	v_mov_b32_e32 v109, v0
	v_mov_b32_e32 v110, v0
	v_mov_b32_e32 v111, v0
	v_mov_b32_e32 v112, v0
	v_mov_b32_e32 v113, v0
	v_mov_b32_e32 v114, v0
	v_mov_b32_e32 v115, v0
	v_mov_b32_e32 v116, v0
	v_mov_b32_e32 v117, v0
	v_mov_b32_e32 v118, v0
	v_mov_b32_e32 v119, v0
	v_mov_b32_e32 v120, v0
	v_mov_b32_e32 v121, v0
	v_mov_b32_e32 v122, v0
	v_mov_b32_e32 v123, v0
	v_mov_b32_e32 v124, v0
	v_mov_b32_e32 v125, v0
	v_mov_b32_e32 v126, v0
	v_mov_b32_e32 v127, v0
	s_barrier
	v_lshlrev_b32_e32 v253, 1, v128
	v_lshlrev_b32_e32 v252, 1, v130
	v_readfirstlane_b32 s32, v133
	.p2align	6

; DEVI f32x4 ozero() { float z = 0.f; asm volatile("" : "+v"(z)); return f32x4{z, z, z, z}; }
; #define WAIT_V(n) asm volatile("s_waitcnt vmcnt(" #n ")" ::: "memory")
; #define BAR __builtin_amdgcn_s_barrier()
; template <int EPI> ...
;     ...
;   const int brow = m0, bcol = n0;
;   const int wid = __builtin_amdgcn_readfirstlane(tid >> 6), lane = tid & 63, wr = wid >> 2, wc = wid & 3, fr = lane & 15, fq = lane >> 4;
;   f32x4 acc[2][2][4][2];
;   {
;     const f32x4 zq = ozero();
; #pragma unroll
;     for (int a_ = 0; a_ < 2; ++a_)
; #pragma unroll
;       for (int b_ = 0; b_ < 2; ++b_)
; #pragma unroll
;         for (int m = 0; m < 4; ++m) { acc[a_][b_][m][0] = zq; acc[a_][b_][m][1] = zq; }
;   }
;   bf16x8 At[4][2], B0[2][2], B1[2][2];
;   const int nt = K / BK;
;     ...
;   if (first) {
;     WAIT_V(0);
;     ISSUE_PRO(brow, bcol);
;   }
;   if (wr == 1) BAR;
;   WAIT_V(10); BAR;
;   WAIT_V(6); BAR;
;   for (int t = 0; t < nt - 2; t += 2) {
.LBB0_165:
	v_and_b32_e32 v133, 15, v132
	v_and_b32_e32 v1, 48, v132
	v_lshlrev_b32_e32 v2, 6, v133
	v_lshlrev_b32_e32 v4, 2, v132
	v_or_b32_e32 v3, v2, v1
	v_and_b32_e32 v4, 32, v4
	s_mov_b32 s20, 0x10000
	v_bitop3_b32 v5, v3, s20, v4 bitop3:0xde
	s_mov_b32 s20, 0x14000
	s_ashr_i32 s68, s62, 6
	v_bitop3_b32 v6, v3, s20, v4 bitop3:0xde
	s_mov_b32 s20, 0x18000
	s_and_b32 s64, s68, 3
	s_waitcnt vmcnt(10)
	s_barrier
	s_waitcnt vmcnt(6)
	v_bitop3_b32 v7, v3, s20, v4 bitop3:0xde
	s_mov_b32 s20, 0x1c000
	v_lshlrev_b32_e32 v8, 6, v132
	s_lshl_b32 s23, s64, 12
	v_bitop3_b32 v2, v2, v4, v1 bitop3:0x36
	s_lshl_b32 s65, s22, 6
	v_bitop3_b32 v3, v3, s20, v4 bitop3:0xde
	s_lshl_b32 s22, s22, 13
	v_and_b32_e32 v8, 0x3c0, v8
	s_ashr_i32 s63, s34, 31
	v_bitop3_b32 v154, v8, v4, v1 bitop3:0x36
	s_or_b32 s66, s22, 0x800
	s_or_b32 s67, s22, 0x1000
	s_or_b32 s69, s22, 0x1800
	s_mov_b32 s70, -2
	s_mov_b64 s[20:21], 0
	v_add_u32_e32 v155, s23, v5
	v_add_u32_e32 v135, s22, v2
	v_add_u32_e32 v152, s23, v6
	v_add_u32_e32 v140, s23, v7
	v_add_u32_e32 v137, s23, v3
	v_mov_b32_e32 v1, v0
	v_mov_b32_e32 v2, v0
	v_mov_b32_e32 v3, v0
	v_mov_b32_e32 v4, v0
	v_mov_b32_e32 v5, v0
	v_mov_b32_e32 v6, v0
	v_mov_b32_e32 v7, v0
	v_mov_b32_e32 v8, v0
	v_mov_b32_e32 v9, v0
	v_mov_b32_e32 v10, v0
	v_mov_b32_e32 v11, v0
	v_mov_b32_e32 v12, v0
	v_mov_b32_e32 v13, v0
	v_mov_b32_e32 v14, v0
	v_mov_b32_e32 v15, v0
	v_mov_b32_e32 v16, v0
	v_mov_b32_e32 v17, v0
	v_mov_b32_e32 v18, v0
	v_mov_b32_e32 v19, v0
	v_mov_b32_e32 v20, v0
	v_mov_b32_e32 v21, v0
	v_mov_b32_e32 v22, v0
	v_mov_b32_e32 v23, v0
	v_mov_b32_e32 v24, v0
	v_mov_b32_e32 v25, v0
	v_mov_b32_e32 v26, v0
	v_mov_b32_e32 v27, v0
	v_mov_b32_e32 v28, v0
	v_mov_b32_e32 v29, v0
	v_mov_b32_e32 v30, v0
	v_mov_b32_e32 v31, v0
	v_mov_b32_e32 v32, v0
	v_mov_b32_e32 v33, v0
	v_mov_b32_e32 v34, v0
	v_mov_b32_e32 v35, v0
	v_mov_b32_e32 v36, v0
	v_mov_b32_e32 v37, v0
	v_mov_b32_e32 v38, v0
	v_mov_b32_e32 v39, v0
	v_mov_b32_e32 v40, v0
	v_mov_b32_e32 v41, v0
	v_mov_b32_e32 v42, v0
	v_mov_b32_e32 v43, v0
	v_mov_b32_e32 v44, v0
	v_mov_b32_e32 v45, v0
	v_mov_b32_e32 v46, v0
	v_mov_b32_e32 v47, v0
	v_mov_b32_e32 v48, v0
	v_mov_b32_e32 v49, v0
	v_mov_b32_e32 v50, v0
	v_mov_b32_e32 v51, v0
	v_mov_b32_e32 v52, v0
	v_mov_b32_e32 v53, v0
	v_mov_b32_e32 v54, v0
	v_mov_b32_e32 v55, v0
	v_mov_b32_e32 v56, v0
	v_mov_b32_e32 v57, v0
	v_mov_b32_e32 v58, v0
	v_mov_b32_e32 v59, v0
	v_mov_b32_e32 v60, v0
	v_mov_b32_e32 v61, v0
	v_mov_b32_e32 v62, v0
	v_mov_b32_e32 v63, v0
	v_mov_b32_e32 v64, v0
	v_mov_b32_e32 v65, v0
	v_mov_b32_e32 v66, v0
	v_mov_b32_e32 v67, v0
	v_mov_b32_e32 v68, v0
	v_mov_b32_e32 v69, v0
	v_mov_b32_e32 v70, v0
	v_mov_b32_e32 v71, v0
	v_mov_b32_e32 v72, v0
	v_mov_b32_e32 v73, v0
	v_mov_b32_e32 v74, v0
	v_mov_b32_e32 v75, v0
	v_mov_b32_e32 v76, v0
	v_mov_b32_e32 v77, v0
	v_mov_b32_e32 v78, v0
	v_mov_b32_e32 v79, v0
	v_mov_b32_e32 v80, v0
	v_mov_b32_e32 v81, v0
	v_mov_b32_e32 v82, v0
	v_mov_b32_e32 v83, v0
	v_mov_b32_e32 v84, v0
	v_mov_b32_e32 v85, v0
	v_mov_b32_e32 v86, v0
	v_mov_b32_e32 v87, v0
	v_mov_b32_e32 v88, v0
	v_mov_b32_e32 v89, v0
	v_mov_b32_e32 v90, v0
	v_mov_b32_e32 v91, v0
	v_mov_b32_e32 v92, v0
	v_mov_b32_e32 v93, v0
	v_mov_b32_e32 v94, v0
	v_mov_b32_e32 v95, v0
	v_mov_b32_e32 v96, v0
	v_mov_b32_e32 v97, v0
	v_mov_b32_e32 v98, v0
	v_mov_b32_e32 v99, v0
	v_mov_b32_e32 v100, v0
	v_mov_b32_e32 v101, v0
	v_mov_b32_e32 v102, v0
	v_mov_b32_e32 v103, v0
	v_mov_b32_e32 v104, v0
	v_mov_b32_e32 v105, v0
	v_mov_b32_e32 v106, v0
	v_mov_b32_e32 v107, v0
	v_mov_b32_e32 v108, v0
	v_mov_b32_e32 v109, v0
	v_mov_b32_e32 v110, v0
	v_mov_b32_e32 v111, v0
	v_mov_b32_e32 v112, v0
	v_mov_b32_e32 v113, v0
	v_mov_b32_e32 v114, v0
	v_mov_b32_e32 v115, v0
	v_mov_b32_e32 v116, v0
	v_mov_b32_e32 v117, v0
	v_mov_b32_e32 v118, v0
	v_mov_b32_e32 v119, v0
	v_mov_b32_e32 v120, v0
	v_mov_b32_e32 v121, v0
	v_mov_b32_e32 v122, v0
	v_mov_b32_e32 v123, v0
	v_mov_b32_e32 v124, v0
	v_mov_b32_e32 v125, v0
	v_mov_b32_e32 v126, v0
	v_mov_b32_e32 v127, v0
	s_barrier
	v_lshlrev_b32_e32 v253, 1, v128
	v_lshlrev_b32_e32 v252, 1, v130
	v_readfirstlane_b32 s32, v129
	.p2align	6

; DEVI f32x4 ozero() { float z = 0.f; asm volatile("" : "+v"(z)); return f32x4{z, z, z, z}; }
; #define WAIT_V(n) asm volatile("s_waitcnt vmcnt(" #n ")" ::: "memory")
; #define BAR __builtin_amdgcn_s_barrier()
; template <int EPI> ...
;     ...
;   const int brow = m0, bcol = n0;
;   const int wid = __builtin_amdgcn_readfirstlane(tid >> 6), lane = tid & 63, wr = wid >> 2, wc = wid & 3, fr = lane & 15, fq = lane >> 4;
;   f32x4 acc[2][2][4][2];
;   {
;     const f32x4 zq = ozero();
; #pragma unroll
;     for (int a_ = 0; a_ < 2; ++a_)
; #pragma unroll
;       for (int b_ = 0; b_ < 2; ++b_)
; #pragma unroll
;         for (int m = 0; m < 4; ++m) { acc[a_][b_][m][0] = zq; acc[a_][b_][m][1] = zq; }
;   }
;   bf16x8 At[4][2], B0[2][2], B1[2][2];
;   const int nt = K / BK;
;     ...
;   if (first) {
;     WAIT_V(0);
;     ISSUE_PRO(brow, bcol);
;   }
;   if (wr == 1) BAR;
;   WAIT_V(10); BAR;
;   WAIT_V(6); BAR;
;   for (int t = 0; t < nt - 2; t += 2) {
.LBB0_415:
	v_and_b32_e32 v132, 15, v133
	v_and_b32_e32 v1, 48, v133
	v_lshlrev_b32_e32 v2, 6, v132
	v_lshlrev_b32_e32 v4, 2, v133
	v_or_b32_e32 v3, v2, v1
	v_and_b32_e32 v4, 32, v4
	s_mov_b32 s12, 0x10000
	v_bitop3_b32 v5, v3, s12, v4 bitop3:0xde
	s_mov_b32 s12, 0x14000
	s_ashr_i32 s1, s62, 6
	v_bitop3_b32 v6, v3, s12, v4 bitop3:0xde
	s_mov_b32 s12, 0x18000
	s_and_b32 s5, s1, 3
	s_waitcnt vmcnt(10)
	s_barrier
	s_waitcnt vmcnt(6)
	v_bitop3_b32 v7, v3, s12, v4 bitop3:0xde
	s_mov_b32 s12, 0x1c000
	v_lshlrev_b32_e32 v8, 6, v133
	s_lshl_b32 s15, s5, 12
	v_bitop3_b32 v2, v2, v4, v1 bitop3:0x36
	s_lshl_b32 s63, s14, 6
	v_bitop3_b32 v3, v3, s12, v4 bitop3:0xde
	s_lshl_b32 s14, s14, 13
	v_and_b32_e32 v8, 0x3c0, v8
	v_bitop3_b32 v154, v8, v4, v1 bitop3:0x36
	s_or_b32 s64, s14, 0x800
	s_or_b32 s65, s14, 0x1000
	s_or_b32 s66, s14, 0x1800
	s_mov_b32 s67, -2
	s_mov_b64 s[12:13], 0
	v_add_u32_e32 v155, s15, v5
	v_add_u32_e32 v135, s14, v2
	v_add_u32_e32 v152, s15, v6
	v_add_u32_e32 v140, s15, v7
	v_add_u32_e32 v137, s15, v3
	v_mov_b32_e32 v1, v0
	v_mov_b32_e32 v2, v0
	v_mov_b32_e32 v3, v0
	v_mov_b32_e32 v4, v0
	v_mov_b32_e32 v5, v0
	v_mov_b32_e32 v6, v0
	v_mov_b32_e32 v7, v0
	v_mov_b32_e32 v8, v0
	v_mov_b32_e32 v9, v0
	v_mov_b32_e32 v10, v0
	v_mov_b32_e32 v11, v0
	v_mov_b32_e32 v12, v0
	v_mov_b32_e32 v13, v0
	v_mov_b32_e32 v14, v0
	v_mov_b32_e32 v15, v0
	v_mov_b32_e32 v16, v0
	v_mov_b32_e32 v17, v0
	v_mov_b32_e32 v18, v0
	v_mov_b32_e32 v19, v0
	v_mov_b32_e32 v20, v0
	v_mov_b32_e32 v21, v0
	v_mov_b32_e32 v22, v0
	v_mov_b32_e32 v23, v0
	v_mov_b32_e32 v24, v0
	v_mov_b32_e32 v25, v0
	v_mov_b32_e32 v26, v0
	v_mov_b32_e32 v27, v0
	v_mov_b32_e32 v28, v0
	v_mov_b32_e32 v29, v0
	v_mov_b32_e32 v30, v0
	v_mov_b32_e32 v31, v0
	v_mov_b32_e32 v32, v0
	v_mov_b32_e32 v33, v0
	v_mov_b32_e32 v34, v0
	v_mov_b32_e32 v35, v0
	v_mov_b32_e32 v36, v0
	v_mov_b32_e32 v37, v0
	v_mov_b32_e32 v38, v0
	v_mov_b32_e32 v39, v0
	v_mov_b32_e32 v40, v0
	v_mov_b32_e32 v41, v0
	v_mov_b32_e32 v42, v0
	v_mov_b32_e32 v43, v0
	v_mov_b32_e32 v44, v0
	v_mov_b32_e32 v45, v0
	v_mov_b32_e32 v46, v0
	v_mov_b32_e32 v47, v0
	v_mov_b32_e32 v48, v0
	v_mov_b32_e32 v49, v0
	v_mov_b32_e32 v50, v0
	v_mov_b32_e32 v51, v0
	v_mov_b32_e32 v52, v0
	v_mov_b32_e32 v53, v0
	v_mov_b32_e32 v54, v0
	v_mov_b32_e32 v55, v0
	v_mov_b32_e32 v56, v0
	v_mov_b32_e32 v57, v0
	v_mov_b32_e32 v58, v0
	v_mov_b32_e32 v59, v0
	v_mov_b32_e32 v60, v0
	v_mov_b32_e32 v61, v0
	v_mov_b32_e32 v62, v0
	v_mov_b32_e32 v63, v0
	v_mov_b32_e32 v64, v0
	v_mov_b32_e32 v65, v0
	v_mov_b32_e32 v66, v0
	v_mov_b32_e32 v67, v0
	v_mov_b32_e32 v68, v0
	v_mov_b32_e32 v69, v0
	v_mov_b32_e32 v70, v0
	v_mov_b32_e32 v71, v0
	v_mov_b32_e32 v72, v0
	v_mov_b32_e32 v73, v0
	v_mov_b32_e32 v74, v0
	v_mov_b32_e32 v75, v0
	v_mov_b32_e32 v76, v0
	v_mov_b32_e32 v77, v0
	v_mov_b32_e32 v78, v0
	v_mov_b32_e32 v79, v0
	v_mov_b32_e32 v80, v0
	v_mov_b32_e32 v81, v0
	v_mov_b32_e32 v82, v0
	v_mov_b32_e32 v83, v0
	v_mov_b32_e32 v84, v0
	v_mov_b32_e32 v85, v0
	v_mov_b32_e32 v86, v0
	v_mov_b32_e32 v87, v0
	v_mov_b32_e32 v88, v0
	v_mov_b32_e32 v89, v0
	v_mov_b32_e32 v90, v0
	v_mov_b32_e32 v91, v0
	v_mov_b32_e32 v92, v0
	v_mov_b32_e32 v93, v0
	v_mov_b32_e32 v94, v0
	v_mov_b32_e32 v95, v0
	v_mov_b32_e32 v96, v0
	v_mov_b32_e32 v97, v0
	v_mov_b32_e32 v98, v0
	v_mov_b32_e32 v99, v0
	v_mov_b32_e32 v100, v0
	v_mov_b32_e32 v101, v0
	v_mov_b32_e32 v102, v0
	v_mov_b32_e32 v103, v0
	v_mov_b32_e32 v104, v0
	v_mov_b32_e32 v105, v0
	v_mov_b32_e32 v106, v0
	v_mov_b32_e32 v107, v0
	v_mov_b32_e32 v108, v0
	v_mov_b32_e32 v109, v0
	v_mov_b32_e32 v110, v0
	v_mov_b32_e32 v111, v0
	v_mov_b32_e32 v112, v0
	v_mov_b32_e32 v113, v0
	v_mov_b32_e32 v114, v0
	v_mov_b32_e32 v115, v0
	v_mov_b32_e32 v116, v0
	v_mov_b32_e32 v117, v0
	v_mov_b32_e32 v118, v0
	v_mov_b32_e32 v119, v0
	v_mov_b32_e32 v120, v0
	v_mov_b32_e32 v121, v0
	v_mov_b32_e32 v122, v0
	v_mov_b32_e32 v123, v0
	v_mov_b32_e32 v124, v0
	v_mov_b32_e32 v125, v0
	v_mov_b32_e32 v126, v0
	v_mov_b32_e32 v127, v0
	s_barrier
	v_lshlrev_b32_e32 v253, 1, v128
	v_lshlrev_b32_e32 v252, 1, v130
	v_readfirstlane_b32 s32, v129
	.p2align	6

; DEVI float sxor(float v, int mask, int lane) { return __int_as_float(__builtin_amdgcn_ds_bpermute((lane ^ mask) << 2, __float_as_int(v))); }
; DEVI f32x4 mfma16(bf16x8 a, bf16x8 b, f32x4 c) { return __builtin_amdgcn_mfma_f32_16x16x32_bf16(a, b, c, 0, 0, 0); }
; DEVI void attn_phase(int wv, const Params& p, char* smem) {
;     ...
;     for (int kt = 0; kt < nkt; ++kt) {
;       const bool more = (kt + 1) < nkt;
;       if (more) {
;         u16* dK = sK + ((kt + 1) & 1) * 64 * 192;
;         u16* dV = sV + ((kt + 1) & 1) * 128 * 64;
;         ATT_STAGE(kt + 1, dK, dV);
;       }
;       const u16* cK = sK + (kt & 1) * 64 * 192;
;       const u16* cV = sV + (kt & 1) * 128 * 64;
;       f32x4 st[4][2];
; #pragma unroll
;       for (int i = 0; i < 4; ++i) { st[i][0] = zq; st[i][1] = zq; }
; #pragma unroll
;       for (int hh = 0; hh < 2; ++hh)
; #pragma unroll
;         for (int ks = 0; ks < 6; ++ks) {
;           const int sw = ((ks * 4 + g) ^ (fr & 7)) << 3;
; #pragma unroll
;           for (int mh = 0; mh < 2; ++mh) {
;             const int mt = hh * 2 + mh;
;             const bf16x8 kf = *(const bf16x8*)(cK + (mt * 16 + fr) * 192 + sw);
;             st[mt][0] = mfma16(kf, qf[0][ks], st[mt][0]);
;             st[mt][1] = mfma16(kf, qf[1][ks], st[mt][1]);
;           }
;         }
; #pragma unroll
;       for (int kk = 0; kk < 2; ++kk) {
;         bf16x8 pf[2];
; #pragma unroll
;         for (int nt = 0; nt < 2; ++nt) {
;           float mx = st[2 * kk][nt][0];
; #pragma unroll
;           for (int mh = 0; mh < 2; ++mh)
; #pragma unroll
;             for (int j = 0; j < 4; ++j) mx = fmaxf(mx, st[2 * kk + mh][nt][j]);
;           if (__builtin_amdgcn_ballot_w64(mx > mrun[nt] + 8.f) != 0ull) {
;             mx = fmaxf(mx, sxor(mx, 16, lane));
;             mx = fmaxf(mx, sxor(mx, 32, lane));
;             const float mnew = mx > mrun[nt] + 8.f ? mx : mrun[nt];
;             const float alpha = __builtin_amdgcn_exp2f(mrun[nt] - mnew);
;             lrun[nt] *= alpha;
; #pragma unroll
;             for (int dt = 0; dt < 8; ++dt) ot[dt][nt] *= alpha;
;             mrun[nt] = mnew;
;           }
;           const float mref = mrun[nt];
;           float ps = 0.f;
; #pragma unroll
;           for (int mh = 0; mh < 2; ++mh)
; #pragma unroll
;             for (int j = 0; j < 4; ++j) {
;               const float pv = __builtin_amdgcn_exp2f(st[2 * kk + mh][nt][j] - mref);
.Lattn_f_end:
	s_add_i32 s15, s15, 1
	s_add_i32 s19, s19, 64
	s_waitcnt vmcnt(0) lgkmcnt(0)
	s_barrier
	s_cmp_eq_u32 s18, s15
	s_cbranch_scc1 .LBB0_986
	v_sub_f32_e32 v184, 0, v181
	v_sub_f32_e32 v185, 0, v181
	v_sub_f32_e32 v186, 0, v181
	v_sub_f32_e32 v187, 0, v181
	v_sub_f32_e32 v188, 0, v180
	v_sub_f32_e32 v189, 0, v180
	v_sub_f32_e32 v190, 0, v180
	v_sub_f32_e32 v191, 0, v180
	v_mov_b32_e32 v253, 0x41000000
	.p2align	6

; DEVI f32x4 ozero() { float z = 0.f; asm volatile("" : "+v"(z)); return f32x4{z, z, z, z}; }
; #define WAIT_V(n) asm volatile("s_waitcnt vmcnt(" #n ")" ::: "memory")
; #define BAR __builtin_amdgcn_s_barrier()
; template <int EPI> ...
;     ...
;   const int brow = m0, bcol = n0;
;   const int wid = __builtin_amdgcn_readfirstlane(tid >> 6), lane = tid & 63, wr = wid >> 2, wc = wid & 3, fr = lane & 15, fq = lane >> 4;
;   f32x4 acc[2][2][4][2];
;   {
;     const f32x4 zq = ozero();
; #pragma unroll
;     for (int a_ = 0; a_ < 2; ++a_)
; #pragma unroll
;       for (int b_ = 0; b_ < 2; ++b_)
; #pragma unroll
;         for (int m = 0; m < 4; ++m) { acc[a_][b_][m][0] = zq; acc[a_][b_][m][1] = zq; }
;   }
;   bf16x8 At[4][2], B0[2][2], B1[2][2];
;   const int nt = K / BK;
;     ...
;   if (first) {
;     WAIT_V(0);
;     ISSUE_PRO(brow, bcol);
;   }
;   if (wr == 1) BAR;
;   WAIT_V(10); BAR;
;   WAIT_V(6); BAR;
;   for (int t = 0; t < nt - 2; t += 2) {
.LBB0_1015:
	v_and_b32_e32 v133, 15, v132
	v_and_b32_e32 v1, 48, v132
	v_lshlrev_b32_e32 v2, 6, v133
	v_lshlrev_b32_e32 v4, 2, v132
	v_or_b32_e32 v3, v2, v1
	v_and_b32_e32 v4, 32, v4
	s_mov_b32 s20, 0x10000
	v_bitop3_b32 v5, v3, s20, v4 bitop3:0xde
	s_mov_b32 s20, 0x14000
	s_ashr_i32 s35, s34, 6
	v_bitop3_b32 v6, v3, s20, v4 bitop3:0xde
	s_mov_b32 s20, 0x18000
	s_and_b32 s9, s35, 3
	s_waitcnt vmcnt(10)
	s_barrier
	s_waitcnt vmcnt(6)
	v_bitop3_b32 v7, v3, s20, v4 bitop3:0xde
	s_mov_b32 s20, 0x1c000
	v_lshlrev_b32_e32 v8, 6, v132
	s_lshl_b32 s23, s9, 12
	v_bitop3_b32 v2, v2, v4, v1 bitop3:0x36
	s_lshl_b32 s62, s22, 6
	v_bitop3_b32 v3, v3, s20, v4 bitop3:0xde
	s_lshl_b32 s22, s22, 13
	v_and_b32_e32 v8, 0x3c0, v8
	v_bitop3_b32 v154, v8, v4, v1 bitop3:0x36
	s_or_b32 s63, s22, 0x800
	s_or_b32 s69, s22, 0x1000
	s_or_b32 s70, s22, 0x1800
	s_mov_b32 s71, -2
	s_mov_b64 s[20:21], 0
	v_add_u32_e32 v155, s23, v5
	v_add_u32_e32 v135, s22, v2
	v_add_u32_e32 v152, s23, v6
	v_add_u32_e32 v140, s23, v7
	v_add_u32_e32 v137, s23, v3
	v_mov_b32_e32 v1, v0
	v_mov_b32_e32 v2, v0
	v_mov_b32_e32 v3, v0
	v_mov_b32_e32 v4, v0
	v_mov_b32_e32 v5, v0
	v_mov_b32_e32 v6, v0
	v_mov_b32_e32 v7, v0
	v_mov_b32_e32 v8, v0
	v_mov_b32_e32 v9, v0
	v_mov_b32_e32 v10, v0
	v_mov_b32_e32 v11, v0
	v_mov_b32_e32 v12, v0
	v_mov_b32_e32 v13, v0
	v_mov_b32_e32 v14, v0
	v_mov_b32_e32 v15, v0
	v_mov_b32_e32 v16, v0
	v_mov_b32_e32 v17, v0
	v_mov_b32_e32 v18, v0
	v_mov_b32_e32 v19, v0
	v_mov_b32_e32 v20, v0
	v_mov_b32_e32 v21, v0
	v_mov_b32_e32 v22, v0
	v_mov_b32_e32 v23, v0
	v_mov_b32_e32 v24, v0
	v_mov_b32_e32 v25, v0
	v_mov_b32_e32 v26, v0
	v_mov_b32_e32 v27, v0
	v_mov_b32_e32 v28, v0
	v_mov_b32_e32 v29, v0
	v_mov_b32_e32 v30, v0
	v_mov_b32_e32 v31, v0
	v_mov_b32_e32 v32, v0
	v_mov_b32_e32 v33, v0
	v_mov_b32_e32 v34, v0
	v_mov_b32_e32 v35, v0
	v_mov_b32_e32 v36, v0
	v_mov_b32_e32 v37, v0
	v_mov_b32_e32 v38, v0
	v_mov_b32_e32 v39, v0
	v_mov_b32_e32 v40, v0
	v_mov_b32_e32 v41, v0
	v_mov_b32_e32 v42, v0
	v_mov_b32_e32 v43, v0
	v_mov_b32_e32 v44, v0
	v_mov_b32_e32 v45, v0
	v_mov_b32_e32 v46, v0
	v_mov_b32_e32 v47, v0
	v_mov_b32_e32 v48, v0
	v_mov_b32_e32 v49, v0
	v_mov_b32_e32 v50, v0
	v_mov_b32_e32 v51, v0
	v_mov_b32_e32 v52, v0
	v_mov_b32_e32 v53, v0
	v_mov_b32_e32 v54, v0
	v_mov_b32_e32 v55, v0
	v_mov_b32_e32 v56, v0
	v_mov_b32_e32 v57, v0
	v_mov_b32_e32 v58, v0
	v_mov_b32_e32 v59, v0
	v_mov_b32_e32 v60, v0
	v_mov_b32_e32 v61, v0
	v_mov_b32_e32 v62, v0
	v_mov_b32_e32 v63, v0
	v_mov_b32_e32 v64, v0
	v_mov_b32_e32 v65, v0
	v_mov_b32_e32 v66, v0
	v_mov_b32_e32 v67, v0
	v_mov_b32_e32 v68, v0
	v_mov_b32_e32 v69, v0
	v_mov_b32_e32 v70, v0
	v_mov_b32_e32 v71, v0
	v_mov_b32_e32 v72, v0
	v_mov_b32_e32 v73, v0
	v_mov_b32_e32 v74, v0
	v_mov_b32_e32 v75, v0
	v_mov_b32_e32 v76, v0
	v_mov_b32_e32 v77, v0
	v_mov_b32_e32 v78, v0
	v_mov_b32_e32 v79, v0
	v_mov_b32_e32 v80, v0
	v_mov_b32_e32 v81, v0
	v_mov_b32_e32 v82, v0
	v_mov_b32_e32 v83, v0
	v_mov_b32_e32 v84, v0
	v_mov_b32_e32 v85, v0
	v_mov_b32_e32 v86, v0
	v_mov_b32_e32 v87, v0
	v_mov_b32_e32 v88, v0
	v_mov_b32_e32 v89, v0
	v_mov_b32_e32 v90, v0
	v_mov_b32_e32 v91, v0
	v_mov_b32_e32 v92, v0
	v_mov_b32_e32 v93, v0
	v_mov_b32_e32 v94, v0
	v_mov_b32_e32 v95, v0
	v_mov_b32_e32 v96, v0
	v_mov_b32_e32 v97, v0
	v_mov_b32_e32 v98, v0
	v_mov_b32_e32 v99, v0
	v_mov_b32_e32 v100, v0
	v_mov_b32_e32 v101, v0
	v_mov_b32_e32 v102, v0
	v_mov_b32_e32 v103, v0
	v_mov_b32_e32 v104, v0
	v_mov_b32_e32 v105, v0
	v_mov_b32_e32 v106, v0
	v_mov_b32_e32 v107, v0
	v_mov_b32_e32 v108, v0
	v_mov_b32_e32 v109, v0
	v_mov_b32_e32 v110, v0
	v_mov_b32_e32 v111, v0
	v_mov_b32_e32 v112, v0
	v_mov_b32_e32 v113, v0
	v_mov_b32_e32 v114, v0
	v_mov_b32_e32 v115, v0
	v_mov_b32_e32 v116, v0
	v_mov_b32_e32 v117, v0
	v_mov_b32_e32 v118, v0
	v_mov_b32_e32 v119, v0
	v_mov_b32_e32 v120, v0
	v_mov_b32_e32 v121, v0
	v_mov_b32_e32 v122, v0
	v_mov_b32_e32 v123, v0
	v_mov_b32_e32 v124, v0
	v_mov_b32_e32 v125, v0
	v_mov_b32_e32 v126, v0
	v_mov_b32_e32 v127, v0
	s_barrier
	v_lshlrev_b32_e32 v253, 1, v128
	v_lshlrev_b32_e32 v252, 1, v130
	v_readfirstlane_b32 s32, v129
	.p2align	6

; DEVI f32x4 ozero() { float z = 0.f; asm volatile("" : "+v"(z)); return f32x4{z, z, z, z}; }
; #define WAIT_V(n) asm volatile("s_waitcnt vmcnt(" #n ")" ::: "memory")
; #define BAR __builtin_amdgcn_s_barrier()
; template <int EPI> ...
;     ...
;   const int brow = m0, bcol = n0;
;   const int wid = __builtin_amdgcn_readfirstlane(tid >> 6), lane = tid & 63, wr = wid >> 2, wc = wid & 3, fr = lane & 15, fq = lane >> 4;
;   f32x4 acc[2][2][4][2];
;   {
;     const f32x4 zq = ozero();
; #pragma unroll
;     for (int a_ = 0; a_ < 2; ++a_)
; #pragma unroll
;       for (int b_ = 0; b_ < 2; ++b_)
; #pragma unroll
;         for (int m = 0; m < 4; ++m) { acc[a_][b_][m][0] = zq; acc[a_][b_][m][1] = zq; }
;   }
;   bf16x8 At[4][2], B0[2][2], B1[2][2];
;   const int nt = K / BK;
;     ...
;   if (first) {
;     WAIT_V(0);
;     ISSUE_PRO(brow, bcol);
;   }
;   if (wr == 1) BAR;
;   WAIT_V(10); BAR;
;   WAIT_V(6); BAR;
;   for (int t = 0; t < nt - 2; t += 2) {
.LBB0_1116:
	v_and_b32_e32 v136, 15, v132
	v_and_b32_e32 v1, 48, v132
	v_lshlrev_b32_e32 v2, 6, v136
	v_lshlrev_b32_e32 v4, 2, v132
	v_or_b32_e32 v3, v2, v1
	v_and_b32_e32 v4, 32, v4
	s_mov_b32 s8, 0x10000
	v_bitop3_b32 v5, v3, s8, v4 bitop3:0xde
	s_mov_b32 s8, 0x14000
	s_ashr_i32 s15, s35, 6
	v_bitop3_b32 v6, v3, s8, v4 bitop3:0xde
	s_mov_b32 s8, 0x18000
	s_and_b32 s19, s15, 3
	s_waitcnt vmcnt(10)
	s_barrier
	s_waitcnt vmcnt(6)
	v_bitop3_b32 v7, v3, s8, v4 bitop3:0xde
	s_mov_b32 s8, 0x1c000
	v_lshlrev_b32_e32 v8, 6, v132
	s_lshl_b32 s23, s19, 12
	v_bitop3_b32 v2, v2, v4, v1 bitop3:0x36
	s_lshl_b32 s21, s22, 6
	v_bitop3_b32 v3, v3, s8, v4 bitop3:0xde
	s_lshl_b32 s22, s22, 13
	v_and_b32_e32 v8, 0x3c0, v8
	v_bitop3_b32 v154, v8, v4, v1 bitop3:0x36
	s_or_b32 s66, s22, 0x800
	s_or_b32 s67, s22, 0x1000
	s_or_b32 s68, s22, 0x1800
	s_mov_b32 s69, -2
	s_mov_b64 s[8:9], 0
	v_add_u32_e32 v155, s23, v5
	v_add_u32_e32 v134, s22, v2
	v_add_u32_e32 v152, s23, v6
	v_add_u32_e32 v140, s23, v7
	v_add_u32_e32 v137, s23, v3
	v_mov_b32_e32 v1, v0
	v_mov_b32_e32 v2, v0
	v_mov_b32_e32 v3, v0
	v_mov_b32_e32 v4, v0
	v_mov_b32_e32 v5, v0
	v_mov_b32_e32 v6, v0
	v_mov_b32_e32 v7, v0
	v_mov_b32_e32 v8, v0
	v_mov_b32_e32 v9, v0
	v_mov_b32_e32 v10, v0
	v_mov_b32_e32 v11, v0
	v_mov_b32_e32 v12, v0
	v_mov_b32_e32 v13, v0
	v_mov_b32_e32 v14, v0
	v_mov_b32_e32 v15, v0
	v_mov_b32_e32 v16, v0
	v_mov_b32_e32 v17, v0
	v_mov_b32_e32 v18, v0
	v_mov_b32_e32 v19, v0
	v_mov_b32_e32 v20, v0
	v_mov_b32_e32 v21, v0
	v_mov_b32_e32 v22, v0
	v_mov_b32_e32 v23, v0
	v_mov_b32_e32 v24, v0
	v_mov_b32_e32 v25, v0
	v_mov_b32_e32 v26, v0
	v_mov_b32_e32 v27, v0
	v_mov_b32_e32 v28, v0
	v_mov_b32_e32 v29, v0
	v_mov_b32_e32 v30, v0
	v_mov_b32_e32 v31, v0
	v_mov_b32_e32 v32, v0
	v_mov_b32_e32 v33, v0
	v_mov_b32_e32 v34, v0
	v_mov_b32_e32 v35, v0
	v_mov_b32_e32 v36, v0
	v_mov_b32_e32 v37, v0
	v_mov_b32_e32 v38, v0
	v_mov_b32_e32 v39, v0
	v_mov_b32_e32 v40, v0
	v_mov_b32_e32 v41, v0
	v_mov_b32_e32 v42, v0
	v_mov_b32_e32 v43, v0
	v_mov_b32_e32 v44, v0
	v_mov_b32_e32 v45, v0
	v_mov_b32_e32 v46, v0
	v_mov_b32_e32 v47, v0
	v_mov_b32_e32 v48, v0
	v_mov_b32_e32 v49, v0
	v_mov_b32_e32 v50, v0
	v_mov_b32_e32 v51, v0
	v_mov_b32_e32 v52, v0
	v_mov_b32_e32 v53, v0
	v_mov_b32_e32 v54, v0
	v_mov_b32_e32 v55, v0
	v_mov_b32_e32 v56, v0
	v_mov_b32_e32 v57, v0
	v_mov_b32_e32 v58, v0
	v_mov_b32_e32 v59, v0
	v_mov_b32_e32 v60, v0
	v_mov_b32_e32 v61, v0
	v_mov_b32_e32 v62, v0
	v_mov_b32_e32 v63, v0
	v_mov_b32_e32 v64, v0
	v_mov_b32_e32 v65, v0
	v_mov_b32_e32 v66, v0
	v_mov_b32_e32 v67, v0
	v_mov_b32_e32 v68, v0
	v_mov_b32_e32 v69, v0
	v_mov_b32_e32 v70, v0
	v_mov_b32_e32 v71, v0
	v_mov_b32_e32 v72, v0
	v_mov_b32_e32 v73, v0
	v_mov_b32_e32 v74, v0
	v_mov_b32_e32 v75, v0
	v_mov_b32_e32 v76, v0
	v_mov_b32_e32 v77, v0
	v_mov_b32_e32 v78, v0
	v_mov_b32_e32 v79, v0
	v_mov_b32_e32 v80, v0
	v_mov_b32_e32 v81, v0
	v_mov_b32_e32 v82, v0
	v_mov_b32_e32 v83, v0
	v_mov_b32_e32 v84, v0
	v_mov_b32_e32 v85, v0
	v_mov_b32_e32 v86, v0
	v_mov_b32_e32 v87, v0
	v_mov_b32_e32 v88, v0
	v_mov_b32_e32 v89, v0
	v_mov_b32_e32 v90, v0
	v_mov_b32_e32 v91, v0
	v_mov_b32_e32 v92, v0
	v_mov_b32_e32 v93, v0
	v_mov_b32_e32 v94, v0
	v_mov_b32_e32 v95, v0
	v_mov_b32_e32 v96, v0
	v_mov_b32_e32 v97, v0
	v_mov_b32_e32 v98, v0
	v_mov_b32_e32 v99, v0
	v_mov_b32_e32 v100, v0
	v_mov_b32_e32 v101, v0
	v_mov_b32_e32 v102, v0
	v_mov_b32_e32 v103, v0
	v_mov_b32_e32 v104, v0
	v_mov_b32_e32 v105, v0
	v_mov_b32_e32 v106, v0
	v_mov_b32_e32 v107, v0
	v_mov_b32_e32 v108, v0
	v_mov_b32_e32 v109, v0
	v_mov_b32_e32 v110, v0
	v_mov_b32_e32 v111, v0
	v_mov_b32_e32 v112, v0
	v_mov_b32_e32 v113, v0
	v_mov_b32_e32 v114, v0
	v_mov_b32_e32 v115, v0
	v_mov_b32_e32 v116, v0
	v_mov_b32_e32 v117, v0
	v_mov_b32_e32 v118, v0
	v_mov_b32_e32 v119, v0
	v_mov_b32_e32 v120, v0
	v_mov_b32_e32 v121, v0
	v_mov_b32_e32 v122, v0
	v_mov_b32_e32 v123, v0
	v_mov_b32_e32 v124, v0
	v_mov_b32_e32 v125, v0
	v_mov_b32_e32 v126, v0
	v_mov_b32_e32 v127, v0
	s_barrier
	.p2align	6

; DEVI u16 f2bf(float f) { return (u16)(pack2(f, 0.f) & 0xffffu); }
; DEVI float bflo(unsigned u) { return __uint_as_float(u << 16); }
; DEVI float bfhi(unsigned u) { return __uint_as_float(u & 0xffff0000u); }
; DEVI void gla_phase(int wv, const Params& p, char* smem) {
;     ...
;       float off0 = 0.f, off1 = 0.f, bt0 = 0.f, bt1 = 0.f;
; #pragma unroll
;       for (int i2 = 0; i2 < 8; ++i2) {
;         const float2 tt = *(const float2*)(sTOT + i2 * 128 + 2 * dp);
;         bt0 += tt.x; bt1 += tt.y;
;         const bool inc = dir == 0 ? (i2 < ig) : (i2 > ig);
;         if (inc) { off0 += tt.x; off1 += tt.y; }
;       }
;       if (ig == 0) *(float2*)(sDEC + 2 * dp) = make_float2(__expf(bt0), __expf(bt1));
;       unsigned ke0[4], ke1[4];
; #pragma unroll
;       for (int r = 0; r < 8; ++r) {
;         const float ea = e0[r] + off0, eb = e1[r] + off1;
;         const float q0 = bflo(qreg[r]), q1 = bfhi(qreg[r]), k0 = bflo(kreg[r]), k1 = bfhi(kreg[r]);
;         *(unsigned*)(sQD + (ig * 8 + r) * 136 + 2 * dp) = pack2(q0 * __expf(ea), q1 * __expf(eb));
;         *(unsigned*)(sKI + (ig * 8 + r) * 136 + 2 * dp) = pack2(k0 * __expf(-ea), k1 * __expf(-eb));
;         const unsigned a0 = f2bf(k0 * __expf(bt0 - ea)), a1 = f2bf(k1 * __expf(bt1 - eb));
;         if (r & 1) { ke0[r >> 1] |= a0 << 16; ke1[r >> 1] |= a1 << 16; }
;         else { ke0[r >> 1] = a0; ke1[r >> 1] = a1; }
;       }
;       *(uint4*)(sKET + (2 * dp) * 72 + ig * 8) = make_uint4(ke0[0], ke0[1], ke0[2], ke0[3]);
;       *(uint4*)(sKET + (2 * dp + 1) * 72 + ig * 8) = make_uint4(ke1[0], ke1[1], ke1[2], ke1[3]);
.LBB0_1339:
	s_or_b64 exec, exec, s[62:63]
	v_cndmask_b32_e64 v109, 0, v109, s[68:69]
	v_cndmask_b32_e64 v108, 0, v108, s[68:69]
	v_add_f32_e32 v110, v108, v110
	v_add_f32_e32 v111, v109, v111
	v_cndmask_b32_e64 v109, v109, v111, s[70:71]
	v_cndmask_b32_e64 v108, v108, v110, s[70:71]
	v_add_f32_e32 v104, v108, v104
	v_add_f32_e32 v105, v109, v105
	v_cndmask_b32_e64 v105, v109, v105, s[72:73]
	v_cndmask_b32_e64 v104, v108, v104, s[72:73]
	v_add_f32_e32 v106, v104, v106
	v_add_f32_e32 v107, v105, v107
	v_cndmask_b32_e64 v105, v105, v107, s[74:75]
	v_cndmask_b32_e64 v104, v104, v106, s[74:75]
	v_add_f32_e32 v106, v104, v112
	v_add_f32_e32 v107, v105, v113
	v_cndmask_b32_e64 v105, v105, v107, s[76:77]
	v_cndmask_b32_e64 v104, v104, v106, s[76:77]
	v_add_f32_e32 v106, v104, v114
	v_add_f32_e32 v107, v105, v115
	v_cndmask_b32_e64 v105, v105, v107, s[78:79]
	v_cndmask_b32_e64 v104, v104, v106, s[78:79]
	v_add_f32_e32 v106, v104, v116
	v_add_f32_e32 v107, v105, v117
	v_cndmask_b32_e64 v105, v105, v107, s[80:81]
	v_cndmask_b32_e64 v104, v104, v106, s[80:81]
	v_add_f32_e32 v106, v104, v118
	v_add_f32_e32 v107, v105, v119
	v_cndmask_b32_e64 v176, v105, v107, s[82:83]
	v_cndmask_b32_e64 v236, v104, v106, s[82:83]
	v_add_f32_e32 v112, v234, v236
	v_add_f32_e32 v113, v233, v176
	v_mul_f32_e32 v108, 0x3fb8aa3b, v112
	v_mul_f32_e32 v109, 0x3fb8aa3b, v113
	v_exp_f32_e32 v108, v108
	v_exp_f32_e32 v109, v109
	s_waitcnt vmcnt(0)
	v_lshlrev_b32_e32 v106, 16, v230
	v_and_b32_e32 v107, 0xffff0000, v230
	v_add_f32_e32 v115, v132, v236
	v_pk_mul_f32 v[106:107], v[108:109], v[106:107]
	v_add_f32_e32 v118, v133, v176
	v_cvt_pk_bf16_f32 v107, v106, v107
	v_mul_f32_e32 v106, 0xbfb8aa3b, v112
	v_mul_f32_e32 v116, 0x3fb8aa3b, v115
	v_mul_f32_e32 v117, 0x3fb8aa3b, v118
	v_exp_f32_e32 v110, v106
	v_mul_f32_e32 v106, 0xbfb8aa3b, v113
	v_exp_f32_e32 v116, v116
	v_exp_f32_e32 v117, v117
	v_exp_f32_e32 v111, v106
	v_sub_f32_e32 v106, v231, v112
	v_mul_f32_e32 v106, 0x3fb8aa3b, v106
	v_exp_f32_e32 v114, v106
	v_sub_f32_e32 v106, v232, v113
	v_lshlrev_b32_e32 v112, 16, v229
	v_and_b32_e32 v113, 0xffff0000, v229
	v_pk_mul_f32 v[112:113], v[116:117], v[112:113]
	v_and_b32_e32 v119, 0xffff0000, v228
	v_cvt_pk_bf16_f32 v112, v112, v113
	ds_write2_b32 v193, v107, v112 offset1:68
	v_mul_f32_e32 v107, 0xbfb8aa3b, v115
	v_exp_f32_e32 v116, v107
	v_mul_f32_e32 v107, 0xbfb8aa3b, v118
	v_exp_f32_e32 v117, v107
	v_sub_f32_e32 v107, v232, v118
	v_mul_f32_e32 v107, 0x3fb8aa3b, v107
	v_exp_f32_e32 v112, v107
	v_sub_f32_e32 v107, v231, v115
	v_mul_f32_e32 v107, 0x3fb8aa3b, v107
	v_exp_f32_e32 v132, v107
	v_add_f32_e32 v107, v130, v236
	v_add_f32_e32 v113, v131, v176
	v_mul_f32_e32 v115, 0x3fb8aa3b, v107
	v_exp_f32_e32 v130, v115
	v_mul_f32_e32 v115, 0x3fb8aa3b, v113
	v_exp_f32_e32 v131, v115
	v_lshlrev_b32_e32 v118, 16, v228
	v_mul_f32_e32 v115, 0xbfb8aa3b, v107
	v_sub_f32_e32 v107, v231, v107
	v_pk_mul_f32 v[118:119], v[130:131], v[118:119]
	v_mul_f32_e32 v107, 0x3fb8aa3b, v107
	v_cvt_pk_bf16_f32 v133, v118, v119
	v_exp_f32_e32 v118, v115
	v_mul_f32_e32 v115, 0xbfb8aa3b, v113
	v_exp_f32_e32 v119, v115
	v_exp_f32_e32 v115, v107
	v_sub_f32_e32 v107, v232, v113
	v_add_f32_e32 v174, v128, v236
	v_add_f32_e32 v113, v129, v176
	v_mul_f32_e32 v130, 0x3fb8aa3b, v174
	v_mul_f32_e32 v131, 0x3fb8aa3b, v113
	v_exp_f32_e32 v130, v130
	v_exp_f32_e32 v131, v131
	v_lshlrev_b32_e32 v128, 16, v227
	v_and_b32_e32 v129, 0xffff0000, v227
	v_add_f32_e32 v227, v126, v236
	v_pk_mul_f32 v[128:129], v[130:131], v[128:129]
	v_add_f32_e32 v228, v127, v176
	v_cvt_pk_bf16_f32 v128, v128, v129
	ds_write2_b32 v193, v133, v128 offset0:136 offset1:204
	v_mul_f32_e32 v128, 0xbfb8aa3b, v174
	v_sub_f32_e32 v130, v231, v174
	v_mul_f32_e32 v174, 0x3fb8aa3b, v227
	v_mul_f32_e32 v175, 0x3fb8aa3b, v228
	v_exp_f32_e32 v174, v174
	v_exp_f32_e32 v175, v175
	v_mul_f32_e32 v130, 0x3fb8aa3b, v130
	v_exp_f32_e32 v133, v130
	v_lshlrev_b32_e32 v130, 16, v226
	v_and_b32_e32 v131, 0xffff0000, v226
	v_pk_mul_f32 v[130:131], v[174:175], v[130:131]
	v_sub_f32_e32 v174, v231, v227
	v_cvt_pk_bf16_f32 v175, v130, v131
	v_mul_f32_e32 v130, 0xbfb8aa3b, v227
	v_add_f32_e32 v227, v124, v236
	v_add_f32_e32 v230, v125, v176
	v_lshlrev_b32_e32 v124, 16, v225
	v_and_b32_e32 v125, 0xffff0000, v225
	v_mul_f32_e32 v225, 0x3fb8aa3b, v227
	v_exp_f32_e32 v234, v225
	v_mul_f32_e32 v225, 0x3fb8aa3b, v230
	v_exp_f32_e32 v235, v225
	v_add_u32_e32 v233, 0x400, v193
	v_add_f32_e32 v238, v120, v236
	v_lshlrev_b32_e32 v120, 16, v223
	v_pk_mul_f32 v[124:125], v[234:235], v[124:125]
	v_lshlrev_b32_e32 v105, 16, v222
	v_cvt_pk_bf16_f32 v124, v124, v125
	ds_write2_b32 v233, v175, v124 offset0:16 offset1:84
	v_sub_f32_e32 v175, v232, v230
	v_mul_f32_e32 v175, 0x3fb8aa3b, v175
	v_exp_f32_e32 v234, v175
	v_sub_f32_e32 v175, v231, v227
	v_mul_f32_e32 v175, 0x3fb8aa3b, v175
	v_mul_f32_e32 v124, 0xbfb8aa3b, v227
	v_mul_f32_e32 v125, 0xbfb8aa3b, v230
	v_exp_f32_e32 v230, v175
	v_add_f32_e32 v175, v122, v236
	v_add_f32_e32 v227, v123, v176
	v_lshlrev_b32_e32 v122, 16, v224
	v_and_b32_e32 v123, 0xffff0000, v224
	v_mul_f32_e32 v224, 0x3fb8aa3b, v175
	v_mul_f32_e32 v225, 0x3fb8aa3b, v227
	v_exp_f32_e32 v224, v224
	v_exp_f32_e32 v225, v225
	v_add_f32_e32 v176, v121, v176
	v_and_b32_e32 v121, 0xffff0000, v223
	v_lshlrev_b32_e32 v104, 16, v221
	v_pk_mul_f32 v[122:123], v[224:225], v[122:123]
	v_mul_f32_e32 v174, 0x3fb8aa3b, v174
	v_cvt_pk_bf16_f32 v235, v122, v123
	v_mul_f32_e32 v122, 0xbfb8aa3b, v175
	v_exp_f32_e32 v224, v122
	v_mul_f32_e32 v122, 0xbfb8aa3b, v227
	v_exp_f32_e32 v225, v122
	v_sub_f32_e32 v122, v231, v175
	v_mul_f32_e32 v122, 0x3fb8aa3b, v122
	v_exp_f32_e32 v175, v122
; DEVI u16 f2bf(float f) { return (u16)(pack2(f, 0.f) & 0xffffu); }
; DEVI float bflo(unsigned u) { return __uint_as_float(u << 16); }
; DEVI float bfhi(unsigned u) { return __uint_as_float(u & 0xffff0000u); }
; DEVI void gla_phase(int wv, const Params& p, char* smem) {
;     ...
;       unsigned ke0[4], ke1[4];
; #pragma unroll
;       for (int r = 0; r < 8; ++r) {
;         const float ea = e0[r] + off0, eb = e1[r] + off1;
;         const float q0 = bflo(qreg[r]), q1 = bfhi(qreg[r]), k0 = bflo(kreg[r]), k1 = bfhi(kreg[r]);
;         *(unsigned*)(sQD + (ig * 8 + r) * 136 + 2 * dp) = pack2(q0 * __expf(ea), q1 * __expf(eb));
;         *(unsigned*)(sKI + (ig * 8 + r) * 136 + 2 * dp) = pack2(k0 * __expf(-ea), k1 * __expf(-eb));
;         const unsigned a0 = f2bf(k0 * __expf(bt0 - ea)), a1 = f2bf(k1 * __expf(bt1 - eb));
;         if (r & 1) { ke0[r >> 1] |= a0 << 16; ke1[r >> 1] |= a1 << 16; }
;         else { ke0[r >> 1] = a0; ke1[r >> 1] = a1; }
;       }
;       *(uint4*)(sKET + (2 * dp) * 72 + ig * 8) = make_uint4(ke0[0], ke0[1], ke0[2], ke0[3]);
;       *(uint4*)(sKET + (2 * dp + 1) * 72 + ig * 8) = make_uint4(ke1[0], ke1[1], ke1[2], ke1[3]);
;       __syncthreads();
	v_sub_f32_e32 v122, v232, v227
	v_mul_f32_e32 v122, 0x3fb8aa3b, v122
	v_exp_f32_e32 v227, v122
	v_mul_f32_e32 v122, 0x3fb8aa3b, v238
	v_mul_f32_e32 v123, 0x3fb8aa3b, v176
	v_exp_f32_e32 v122, v122
	v_exp_f32_e32 v123, v123
	v_lshlrev_b32_e32 v109, 16, v220
	v_lshlrev_b32_e32 v108, 16, v167
	v_exp_f32_e32 v174, v174
	v_pk_mul_f32 v[120:121], v[122:123], v[120:121]
	v_pk_mul_f32 v[114:115], v[114:115], v[104:105]
	v_cvt_pk_bf16_f32 v120, v120, v121
	ds_write2_b32 v233, v235, v120 offset0:152 offset1:220
	v_mul_f32_e32 v120, 0xbfb8aa3b, v238
	v_exp_f32_e32 v236, v120
	v_mul_f32_e32 v120, 0xbfb8aa3b, v176
	v_exp_f32_e32 v237, v120
	v_sub_f32_e32 v120, v232, v176
	v_mul_f32_e32 v120, 0x3fb8aa3b, v120
	v_exp_f32_e32 v235, v120
	v_sub_f32_e32 v120, v231, v238
	v_mul_f32_e32 v120, 0x3fb8aa3b, v120
	v_exp_f32_e32 v231, v120
	v_cvt_pk_bf16_f32 v120, v114, v115
	v_pk_mul_f32 v[114:115], v[132:133], v[108:109]
	v_lshlrev_b32_e32 v127, 16, v219
	v_cvt_pk_bf16_f32 v114, v114, v115
	v_lshlrev_b32_e32 v126, 16, v166
	v_and_b32_e32 v115, 0xffff0000, v114
	v_lshlrev_b32_e32 v114, 16, v114
	v_mul_f32_e32 v131, 0xbfb8aa3b, v228
	v_sub_f32_e32 v226, v232, v228
	v_lshlrev_b32_e32 v229, 16, v135
	v_lshlrev_b32_e32 v228, 16, v134
	v_or_b32_sdwa v121, v115, v120 dst_sel:DWORD dst_unused:UNUSED_PAD src0_sel:DWORD src1_sel:WORD_1
	v_or_b32_sdwa v120, v114, v120 dst_sel:DWORD dst_unused:UNUSED_PAD src0_sel:DWORD src1_sel:WORD_0
	v_pk_mul_f32 v[114:115], v[174:175], v[126:127]
	v_mul_f32_e32 v106, 0x3fb8aa3b, v106
	v_mul_f32_e32 v107, 0x3fb8aa3b, v107
	v_cvt_pk_bf16_f32 v122, v114, v115
	v_pk_mul_f32 v[114:115], v[230:231], v[228:229]
	v_exp_f32_e32 v106, v106
	v_exp_f32_e32 v107, v107
	v_mul_f32_e32 v129, 0xbfb8aa3b, v113
	v_sub_f32_e32 v113, v232, v113
	v_cvt_pk_bf16_f32 v114, v114, v115
	v_mul_f32_e32 v113, 0x3fb8aa3b, v113
	v_and_b32_e32 v115, 0xffff0000, v114
	v_lshlrev_b32_e32 v114, 16, v114
	v_exp_f32_e32 v128, v128
	v_exp_f32_e32 v129, v129
	v_exp_f32_e32 v113, v113
	v_or_b32_sdwa v123, v115, v122 dst_sel:DWORD dst_unused:UNUSED_PAD src0_sel:DWORD src1_sel:WORD_1
	v_or_b32_sdwa v122, v114, v122 dst_sel:DWORD dst_unused:UNUSED_PAD src0_sel:DWORD src1_sel:WORD_0
	v_and_b32_e32 v115, 0xffff0000, v222
	v_and_b32_e32 v114, 0xffff0000, v221
	v_mov_b32_e32 v132, v104
	v_mov_b32_e32 v133, v114
	v_mov_b32_e32 v104, v105
	v_mov_b32_e32 v105, v115
	v_pk_mul_f32 v[110:111], v[110:111], v[132:133]
	v_and_b32_e32 v133, 0xffff0000, v220
	v_pk_mul_f32 v[118:119], v[118:119], v[104:105]
	v_pk_mul_f32 v[104:105], v[106:107], v[114:115]
	v_and_b32_e32 v132, 0xffff0000, v167
	v_mov_b32_e32 v174, v108
	v_cvt_pk_bf16_f32 v108, v104, v105
	v_mov_b32_e32 v104, v109
	v_mov_b32_e32 v105, v133
	v_pk_mul_f32 v[106:107], v[128:129], v[104:105]
	v_pk_mul_f32 v[104:105], v[112:113], v[132:133]
	v_mul_f32_e32 v226, 0x3fb8aa3b, v226
	v_mov_b32_e32 v175, v132
	v_cvt_pk_bf16_f32 v104, v104, v105
	v_exp_f32_e32 v226, v226
	v_pk_mul_f32 v[116:117], v[116:117], v[174:175]
	v_and_b32_e32 v105, 0xffff0000, v104
	v_lshlrev_b32_e32 v104, 16, v104
	v_or_b32_sdwa v105, v105, v108 dst_sel:DWORD dst_unused:UNUSED_PAD src0_sel:DWORD src1_sel:WORD_1
	v_or_b32_sdwa v104, v104, v108 dst_sel:DWORD dst_unused:UNUSED_PAD src0_sel:DWORD src1_sel:WORD_0
	v_cvt_pk_bf16_f32 v108, v110, v111
	v_cvt_pk_bf16_f32 v109, v116, v117
	ds_write2_b32 v194, v108, v109 offset1:68
	v_cvt_pk_bf16_f32 v108, v118, v119
	v_cvt_pk_bf16_f32 v106, v106, v107
	v_exp_f32_e32 v130, v130
	v_exp_f32_e32 v131, v131
	v_exp_f32_e32 v124, v124
	v_exp_f32_e32 v125, v125
	ds_write2_b32 v194, v108, v106 offset0:136 offset1:204
	v_and_b32_e32 v107, 0xffff0000, v219
	v_and_b32_e32 v106, 0xffff0000, v166
	v_mov_b32_e32 v109, v106
	v_and_b32_e32 v111, 0xffff0000, v135
	v_mov_b32_e32 v115, v107
	v_pk_mul_f32 v[106:107], v[226:227], v[106:107]
	v_and_b32_e32 v110, 0xffff0000, v134
	v_cvt_pk_bf16_f32 v118, v106, v107
	v_mov_b32_e32 v106, v229
	v_mov_b32_e32 v107, v111
	v_mov_b32_e32 v108, v126
	v_mov_b32_e32 v112, v228
	v_mov_b32_e32 v113, v110
	v_pk_mul_f32 v[116:117], v[236:237], v[106:107]
	v_pk_mul_f32 v[106:107], v[234:235], v[110:111]
	v_pk_mul_f32 v[108:109], v[130:131], v[108:109]
	v_pk_mul_f32 v[112:113], v[124:125], v[112:113]
	v_mov_b32_e32 v114, v127
	v_cvt_pk_bf16_f32 v106, v106, v107
	v_pk_mul_f32 v[114:115], v[224:225], v[114:115]
	v_and_b32_e32 v107, 0xffff0000, v106
	v_lshlrev_b32_e32 v106, 16, v106
	v_cvt_pk_bf16_f32 v108, v108, v109
	v_cvt_pk_bf16_f32 v109, v112, v113
	v_add_u32_e32 v110, 0x400, v194
	v_or_b32_sdwa v107, v107, v118 dst_sel:DWORD dst_unused:UNUSED_PAD src0_sel:DWORD src1_sel:WORD_1
	v_or_b32_sdwa v106, v106, v118 dst_sel:DWORD dst_unused:UNUSED_PAD src0_sel:DWORD src1_sel:WORD_0
	ds_write2_b32 v110, v108, v109 offset0:16 offset1:84
	v_cvt_pk_bf16_f32 v108, v114, v115
	v_cvt_pk_bf16_f32 v109, v116, v117
	ds_write2_b32 v110, v108, v109 offset0:152 offset1:220
	ds_write_b128 v185, v[120:123]
	ds_write_b128 v185, v[104:107] offset:144
	s_waitcnt lgkmcnt(0)
	s_barrier
; DEVI u16 f2bf(float f) { return (u16)(pack2(f, 0.f) & 0xffffu); }
; DEVI void gla_phase(int wv, const Params& p, char* smem) {
;     ...
;       {
;         const int jt = wave >> 1, it0 = (wave & 1) * 2;
;         f32x4 at[2] = {zq, zq};
; #pragma unroll
;         for (int ks = 0; ks < 4; ++ks) {
;           const bf16x8 kf = *(const bf16x8*)(sKI + (jt * 16 + fr) * 136 + ks * 32 + g * 8);
; #pragma unroll
;           for (int ii = 0; ii < 2; ++ii) {
;             const bf16x8 qq = *(const bf16x8*)(sQD + ((it0 + ii) * 16 + fr) * 136 + ks * 32 + g * 8);
;             at[ii] = mfma16(kf, qq, at[ii]);
;           }
;         }
; #pragma unroll
;         for (int ii = 0; ii < 2; ++ii) {
;           const int i = (it0 + ii) * 16 + fr;
;           float m[4];
; #pragma unroll
;           for (int jj = 0; jj < 4; ++jj) {
;             const int j = jt * 16 + g * 4 + jj;
;             const bool keep = dir == 0 ? (j <= i) : (j > i);
;             m[jj] = keep ? at[ii][jj] : 0.f;
;           }
;           uint2 v;
;           v.x = pack2(m[0], m[1]);
;           v.y = pack2(m[2], m[3]);
;           *(uint2*)(sAM + i * 72 + jt * 16 + g * 4) = v;
;         }
;       }
;       __syncthreads();
;       {
;         bf16x8 sf[2][4];
; #pragma unroll
;         for (int nt = 0; nt < 2; ++nt)
; #pragma unroll
;           for (int ks = 0; ks < 4; ++ks)
;             sf[nt][ks] = *(const bf16x8*)(sST + (wave * 32 + nt * 16 + fr) * 136 + ks * 32 + g * 8);
; #pragma unroll
;         for (int mt = 0; mt < 4; ++mt) {
;           f32x4 oa[2] = {zq, zq};
; #pragma unroll
;           for (int kk = 0; kk < 2; ++kk) {
;             const bf16x8 af = *(const bf16x8*)(sAM + (mt * 16 + fr) * 72 + kk * 32 + g * 8);
;             oa[0] = mfma16(af, vf[0][kk], oa[0]);
;             oa[1] = mfma16(af, vf[1][kk], oa[1]);
;           }
; #pragma unroll
;           for (int ks = 0; ks < 4; ++ks) {
;             const bf16x8 qq = *(const bf16x8*)(sQD + (mt * 16 + fr) * 136 + ks * 32 + g * 8);
;             oa[0] = mfma16(qq, sf[0][ks], oa[0]);
;             oa[1] = mfma16(qq, sf[1][ks], oa[1]);
;           }
; #pragma unroll
;           for (int nt = 0; nt < 2; ++nt)
; #pragma unroll
;             for (int jj = 0; jj < 4; ++jj)
;               O[(size_t)(tbase + mt * 16 + g * 4 + jj) * 1024 + h * 256 + wave * 32 + nt * 16 + fr] = f2bf(oa[nt][jj]);
	ds_read_b128 v[104:107], v186
	ds_read_b128 v[108:111], v200
	ds_read_b128 v[112:115], v200 offset:4352
	s_waitcnt lgkmcnt(1)
	v_mfma_f32_16x16x32_bf16 v[108:111], v[104:107], v[108:111], v[0:3]
	s_add_i32 s44, s17, -1
	s_and_b64 s[62:63], s[66:67], exec
	s_cselect_b32 s44, s44, s16
	s_waitcnt lgkmcnt(0)
	v_mfma_f32_16x16x32_bf16 v[104:107], v[104:107], v[112:115], v[0:3]
	ds_read_b128 v[112:115], v186 offset:64
	ds_read_b128 v[116:119], v200 offset:64
	v_lshl_add_u32 v166, s44, 6, v148
	v_ashrrev_i32_e32 v167, 31, v166
	s_waitcnt lgkmcnt(0)
	v_mfma_f32_16x16x32_bf16 v[108:111], v[112:115], v[116:119], v[108:111]
	ds_read_b128 v[116:119], v200 offset:4416
	v_lshlrev_b64 v[174:175], 11, v[166:167]
	v_lshl_add_u64 v[174:175], v[162:163], 0, v[174:175]
	s_waitcnt lgkmcnt(0)
	v_mfma_f32_16x16x32_bf16 v[104:107], v[112:115], v[116:119], v[104:107]
	ds_read_b128 v[112:115], v186 offset:128
	ds_read_b128 v[116:119], v200 offset:128
	s_movk_i32 s44, 0x1000
	s_mov_b64 s[62:63], 0x1000
	s_waitcnt lgkmcnt(0)
	v_mfma_f32_16x16x32_bf16 v[108:111], v[112:115], v[116:119], v[108:111]
	ds_read_b128 v[116:119], v200 offset:4480
	s_add_i32 s16, s16, -1
	s_add_i32 s17, s17, 1
	s_waitcnt lgkmcnt(0)
	v_mfma_f32_16x16x32_bf16 v[104:107], v[112:115], v[116:119], v[104:107]
	ds_read_b128 v[112:115], v186 offset:192
	ds_read_b128 v[116:119], v200 offset:192
	s_cmp_eq_u32 s16, -1
	v_mov_b32_e32 v219, v209
	s_waitcnt lgkmcnt(0)
	v_mfma_f32_16x16x32_bf16 v[108:111], v[112:115], v[116:119], v[108:111]
	ds_read_b128 v[116:119], v200 offset:4544
	s_waitcnt lgkmcnt(0)
	v_mfma_f32_16x16x32_bf16 v[104:107], v[112:115], v[116:119], v[104:107]
	s_nop 4
	v_cndmask_b32_e64 v108, 0, v108, s[84:85]
	v_cndmask_b32_e64 v109, 0, v109, s[86:87]
	v_cndmask_b32_e64 v110, 0, v110, s[88:89]
	v_cndmask_b32_e64 v111, 0, v111, s[90:91]
	v_cvt_pk_bf16_f32 v108, v108, v109
	v_cvt_pk_bf16_f32 v109, v110, v111
	v_cndmask_b32_e64 v104, 0, v104, s[92:93]
	v_cndmask_b32_e64 v105, 0, v105, s[94:95]
	v_cndmask_b32_e64 v106, 0, v106, s[96:97]
	v_cndmask_b32_e64 v107, 0, v107, s[64:65]
	ds_write_b64 v201, v[108:109]
	v_cvt_pk_bf16_f32 v104, v104, v105
	v_cvt_pk_bf16_f32 v105, v106, v107
	v_add_u32_e32 v108, v144, v195
	ds_write_b64 v201, v[104:105] offset:2304
	s_waitcnt lgkmcnt(0)
	s_barrier
	ds_read_b128 v[128:131], v108
	ds_read_b128 v[116:119], v108 offset:64
	ds_read_b128 v[112:115], v108 offset:128
	ds_read_b128 v[104:107], v108 offset:192
	ds_read_b128 v[132:135], v108 offset:4352
	ds_read_b128 v[124:127], v108 offset:4416
	ds_read_b128 v[120:123], v108 offset:4480
	ds_read_b128 v[108:111], v108 offset:4544
	ds_read_b128 v[220:223], v202
	ds_read_b128 v[228:231], v202 offset:64
	s_waitcnt lgkmcnt(1)
	v_mfma_f32_16x16x32_bf16 v[224:227], v[220:223], v[20:23], v[0:3]
	v_mfma_f32_16x16x32_bf16 v[220:223], v[220:223], v[16:19], v[0:3]
	s_waitcnt lgkmcnt(0)
	v_mfma_f32_16x16x32_bf16 v[224:227], v[228:231], v[12:15], v[224:227]
	v_mfma_f32_16x16x32_bf16 v[220:223], v[228:231], v[8:11], v[220:223]
	ds_read_b128 v[228:231], v203
	s_waitcnt lgkmcnt(0)
	v_mfma_f32_16x16x32_bf16 v[224:227], v[228:231], v[128:131], v[224:227]
	v_mfma_f32_16x16x32_bf16 v[220:223], v[228:231], v[132:135], v[220:223]
	ds_read_b128 v[228:231], v203 offset:64
	s_waitcnt lgkmcnt(0)
	v_mfma_f32_16x16x32_bf16 v[224:227], v[228:231], v[116:119], v[224:227]
	v_mfma_f32_16x16x32_bf16 v[220:223], v[228:231], v[124:127], v[220:223]
	ds_read_b128 v[228:231], v203 offset:128
	s_waitcnt lgkmcnt(0)
	v_mfma_f32_16x16x32_bf16 v[224:227], v[228:231], v[112:115], v[224:227]
	v_mfma_f32_16x16x32_bf16 v[220:223], v[228:231], v[120:123], v[220:223]
	ds_read_b128 v[228:231], v203 offset:192
	s_waitcnt lgkmcnt(0)
	v_mfma_f32_16x16x32_bf16 v[224:227], v[228:231], v[104:107], v[224:227]
	s_nop 7
	v_cvt_pk_bf16_f32 v167, v225, s0
	v_mfma_f32_16x16x32_bf16 v[220:223], v[228:231], v[108:111], v[220:223]
	v_add_co_u32_e32 v228, vcc, s44, v174
	global_store_short v[174:175], v167, off offset:2048
	v_cvt_pk_bf16_f32 v167, v226, s0
	v_addc_co_u32_e32 v229, vcc, 0, v175, vcc
	global_store_short v[228:229], v167, off
	v_cvt_pk_bf16_f32 v167, v227, s0
	global_store_short v[228:229], v167, off offset:2048
	s_nop 0
	v_cvt_pk_bf16_f32 v167, v220, s0
	global_store_short v[174:175], v167, off offset:32
	v_cvt_pk_bf16_f32 v167, v221, s0
	v_cvt_pk_bf16_f32 v176, v224, s0
	v_lshl_add_u64 v[224:225], v[174:175], 0, s[62:63]
	s_mov_b64 s[62:63], 0x1800
	global_store_short v[174:175], v167, off offset:2080
	v_cvt_pk_bf16_f32 v167, v222, s0
	v_lshl_add_u64 v[226:227], v[174:175], 0, s[62:63]
	global_store_short v[224:225], v167, off offset:32
	v_cvt_pk_bf16_f32 v167, v223, s0
	global_store_short v[174:175], v176, off
	global_store_short v[226:227], v167, off offset:32
	ds_read_b128 v[220:223], v202 offset:2304
	ds_read_b128 v[228:231], v202 offset:2368
	s_waitcnt lgkmcnt(0)
	v_mfma_f32_16x16x32_bf16 v[224:227], v[220:223], v[20:23], v[0:3]
	v_add_u32_e32 v174, 16, v166
	v_ashrrev_i32_e32 v175, 31, v174
	v_lshlrev_b64 v[174:175], 11, v[174:175]
	v_mfma_f32_16x16x32_bf16 v[220:223], v[220:223], v[16:19], v[0:3]
	v_lshl_add_u64 v[174:175], v[162:163], 0, v[174:175]
	v_mfma_f32_16x16x32_bf16 v[224:227], v[228:231], v[12:15], v[224:227]
	v_mfma_f32_16x16x32_bf16 v[220:223], v[228:231], v[8:11], v[220:223]
	ds_read_b128 v[228:231], v203 offset:4352
	s_waitcnt lgkmcnt(0)
	v_mfma_f32_16x16x32_bf16 v[224:227], v[228:231], v[128:131], v[224:227]
	v_mfma_f32_16x16x32_bf16 v[220:223], v[228:231], v[132:135], v[220:223]
	ds_read_b128 v[228:231], v203 offset:4416
	s_waitcnt lgkmcnt(0)
; DEVI u16 f2bf(float f) { return (u16)(pack2(f, 0.f) & 0xffffu); }
; DEVI f32x4 mfma16(bf16x8 a, bf16x8 b, f32x4 c) { return __builtin_amdgcn_mfma_f32_16x16x32_bf16(a, b, c, 0, 0, 0); }
; DEVI void gla_phase(int wv, const Params& p, char* smem) {
;     ...
;         for (int mt = 0; mt < 4; ++mt) {
;           f32x4 oa[2] = {zq, zq};
; #pragma unroll
;           for (int kk = 0; kk < 2; ++kk) {
;             const bf16x8 af = *(const bf16x8*)(sAM + (mt * 16 + fr) * 72 + kk * 32 + g * 8);
;             oa[0] = mfma16(af, vf[0][kk], oa[0]);
;             oa[1] = mfma16(af, vf[1][kk], oa[1]);
;           }
; #pragma unroll
;           for (int ks = 0; ks < 4; ++ks) {
;             const bf16x8 qq = *(const bf16x8*)(sQD + (mt * 16 + fr) * 136 + ks * 32 + g * 8);
;             oa[0] = mfma16(qq, sf[0][ks], oa[0]);
;             oa[1] = mfma16(qq, sf[1][ks], oa[1]);
;           }
; #pragma unroll
;           for (int nt = 0; nt < 2; ++nt)
; #pragma unroll
;             for (int jj = 0; jj < 4; ++jj)
;               O[(size_t)(tbase + mt * 16 + g * 4 + jj) * 1024 + h * 256 + wave * 32 + nt * 16 + fr] = f2bf(oa[nt][jj]);
	v_mfma_f32_16x16x32_bf16 v[224:227], v[228:231], v[116:119], v[224:227]
	v_mfma_f32_16x16x32_bf16 v[220:223], v[228:231], v[124:127], v[220:223]
	ds_read_b128 v[228:231], v203 offset:4480
	s_waitcnt lgkmcnt(0)
	v_mfma_f32_16x16x32_bf16 v[224:227], v[228:231], v[112:115], v[224:227]
	v_mfma_f32_16x16x32_bf16 v[220:223], v[228:231], v[120:123], v[220:223]
	ds_read_b128 v[228:231], v203 offset:4544
	s_waitcnt lgkmcnt(0)
	v_mfma_f32_16x16x32_bf16 v[224:227], v[228:231], v[104:107], v[224:227]
	s_nop 7
	v_cvt_pk_bf16_f32 v167, v224, s0
	v_add_u32_e32 v224, 17, v166
	v_mfma_f32_16x16x32_bf16 v[220:223], v[228:231], v[108:111], v[220:223]
	global_store_short v[174:175], v167, off
	v_cvt_pk_bf16_f32 v167, v225, s0
	v_ashrrev_i32_e32 v225, 31, v224
	v_add_u32_e32 v228, 18, v166
	v_lshlrev_b64 v[224:225], 11, v[224:225]
	v_ashrrev_i32_e32 v229, 31, v228
	v_lshl_add_u64 v[224:225], v[162:163], 0, v[224:225]
	v_lshlrev_b64 v[228:229], 11, v[228:229]
	global_store_short v[224:225], v167, off
	v_cvt_pk_bf16_f32 v167, v226, s0
	v_lshl_add_u64 v[228:229], v[162:163], 0, v[228:229]
	v_add_u32_e32 v226, 19, v166
	global_store_short v[228:229], v167, off
	v_cvt_pk_bf16_f32 v167, v227, s0
	v_ashrrev_i32_e32 v227, 31, v226
	v_lshlrev_b64 v[226:227], 11, v[226:227]
	v_lshl_add_u64 v[226:227], v[162:163], 0, v[226:227]
	global_store_short v[226:227], v167, off
	v_cvt_pk_bf16_f32 v167, v220, s0
	global_store_short v[174:175], v167, off offset:32
	v_cvt_pk_bf16_f32 v167, v221, s0
	global_store_short v[224:225], v167, off offset:32
	v_cvt_pk_bf16_f32 v167, v222, s0
	global_store_short v[228:229], v167, off offset:32
	v_cvt_pk_bf16_f32 v167, v223, s0
	global_store_short v[226:227], v167, off offset:32
	ds_read_b128 v[220:223], v202 offset:4608
	ds_read_b128 v[228:231], v202 offset:4672
	s_waitcnt lgkmcnt(0)
	v_mfma_f32_16x16x32_bf16 v[224:227], v[220:223], v[20:23], v[0:3]
	v_add_u32_e32 v174, 32, v166
	v_ashrrev_i32_e32 v175, 31, v174
	v_lshlrev_b64 v[174:175], 11, v[174:175]
	v_mfma_f32_16x16x32_bf16 v[220:223], v[220:223], v[16:19], v[0:3]
	v_lshl_add_u64 v[174:175], v[162:163], 0, v[174:175]
	v_mfma_f32_16x16x32_bf16 v[224:227], v[228:231], v[12:15], v[224:227]
	v_mfma_f32_16x16x32_bf16 v[220:223], v[228:231], v[8:11], v[220:223]
	ds_read_b128 v[228:231], v203 offset:8704
	s_waitcnt lgkmcnt(0)
	v_mfma_f32_16x16x32_bf16 v[224:227], v[228:231], v[128:131], v[224:227]
	v_mfma_f32_16x16x32_bf16 v[220:223], v[228:231], v[132:135], v[220:223]
	ds_read_b128 v[228:231], v203 offset:8768
	s_waitcnt lgkmcnt(0)
	v_mfma_f32_16x16x32_bf16 v[224:227], v[228:231], v[116:119], v[224:227]
	v_mfma_f32_16x16x32_bf16 v[220:223], v[228:231], v[124:127], v[220:223]
	ds_read_b128 v[228:231], v203 offset:8832
	s_waitcnt lgkmcnt(0)
	v_mfma_f32_16x16x32_bf16 v[224:227], v[228:231], v[112:115], v[224:227]
	v_mfma_f32_16x16x32_bf16 v[220:223], v[228:231], v[120:123], v[220:223]
	ds_read_b128 v[228:231], v203 offset:8896
	s_waitcnt lgkmcnt(0)
	v_mfma_f32_16x16x32_bf16 v[224:227], v[228:231], v[104:107], v[224:227]
	s_nop 7
	v_cvt_pk_bf16_f32 v167, v224, s0
	v_add_u32_e32 v224, 33, v166
	v_mfma_f32_16x16x32_bf16 v[220:223], v[228:231], v[108:111], v[220:223]
	global_store_short v[174:175], v167, off
	v_cvt_pk_bf16_f32 v167, v225, s0
	v_ashrrev_i32_e32 v225, 31, v224
	v_add_u32_e32 v228, 34, v166
	v_lshlrev_b64 v[224:225], 11, v[224:225]
	v_ashrrev_i32_e32 v229, 31, v228
	v_lshl_add_u64 v[224:225], v[162:163], 0, v[224:225]
	v_lshlrev_b64 v[228:229], 11, v[228:229]
	global_store_short v[224:225], v167, off
	v_cvt_pk_bf16_f32 v167, v226, s0
	v_lshl_add_u64 v[228:229], v[162:163], 0, v[228:229]
	v_add_u32_e32 v226, 35, v166
	global_store_short v[228:229], v167, off
	v_cvt_pk_bf16_f32 v167, v227, s0
	v_ashrrev_i32_e32 v227, 31, v226
	v_lshlrev_b64 v[226:227], 11, v[226:227]
	v_lshl_add_u64 v[226:227], v[162:163], 0, v[226:227]
	global_store_short v[226:227], v167, off
	v_cvt_pk_bf16_f32 v167, v220, s0
	global_store_short v[174:175], v167, off offset:32
	v_cvt_pk_bf16_f32 v167, v221, s0
	global_store_short v[224:225], v167, off offset:32
	v_cvt_pk_bf16_f32 v167, v222, s0
	global_store_short v[228:229], v167, off offset:32
	v_cvt_pk_bf16_f32 v167, v223, s0
	global_store_short v[226:227], v167, off offset:32
	ds_read_b128 v[220:223], v202 offset:6912
	ds_read_b128 v[228:231], v202 offset:6976
	s_waitcnt lgkmcnt(0)
	v_mfma_f32_16x16x32_bf16 v[224:227], v[220:223], v[20:23], v[0:3]
	v_mov_b32_e32 v167, v157
	v_mfma_f32_16x16x32_bf16 v[220:223], v[220:223], v[16:19], v[0:3]
	v_mfma_f32_16x16x32_bf16 v[224:227], v[228:231], v[12:15], v[224:227]
	v_mfma_f32_16x16x32_bf16 v[220:223], v[228:231], v[8:11], v[220:223]
	ds_read_b128 v[228:231], v203 offset:13056
	s_waitcnt lgkmcnt(0)
	v_mfma_f32_16x16x32_bf16 v[132:135], v[228:231], v[132:135], v[220:223]
	s_nop 4
	ds_read_b128 v[220:223], v203 offset:13120
	v_mfma_f32_16x16x32_bf16 v[128:131], v[228:231], v[128:131], v[224:227]
	v_mov_b32_e32 v230, v210
	v_mov_b32_e32 v229, v212
	v_mov_b32_e32 v228, v213
	s_waitcnt lgkmcnt(0)
	v_mfma_f32_16x16x32_bf16 v[116:119], v[220:223], v[116:119], v[128:131]
	v_mov_b32_e32 v227, v214
	s_nop 1
	ds_read_b128 v[128:131], v203 offset:13184
	v_mov_b32_e32 v226, v215
	v_mfma_f32_16x16x32_bf16 v[124:127], v[220:223], v[124:127], v[132:135]
	v_mov_b32_e32 v225, v216
	v_mov_b32_e32 v224, v217
	v_mov_b32_e32 v223, v218
	s_waitcnt lgkmcnt(0)
	v_mfma_f32_16x16x32_bf16 v[112:115], v[128:131], v[112:115], v[116:119]
	v_mov_b32_e32 v220, v207
	v_mov_b32_e32 v221, v155
	v_mov_b32_e32 v222, v205
	v_mfma_f32_16x16x32_bf16 v[116:119], v[128:131], v[120:123], v[124:127]
	ds_read_b128 v[120:123], v203 offset:13248
	v_mov_b32_e32 v134, v208
	v_mov_b32_e32 v135, v211
	s_waitcnt lgkmcnt(0)
; DEVI u16 f2bf(float f) { return (u16)(pack2(f, 0.f) & 0xffffu); }
; DEVI f32x4 mfma16(bf16x8 a, bf16x8 b, f32x4 c) { return __builtin_amdgcn_mfma_f32_16x16x32_bf16(a, b, c, 0, 0, 0); }
; DEVI void gla_phase(int wv, const Params& p, char* smem) {
;     ...
;           for (int nt = 0; nt < 2; ++nt)
; #pragma unroll
;             for (int jj = 0; jj < 4; ++jj)
;               O[(size_t)(tbase + mt * 16 + g * 4 + jj) * 1024 + h * 256 + wave * 32 + nt * 16 + fr] = f2bf(oa[nt][jj]);
;         }
; #pragma unroll
;         for (int mt = 0; mt < 8; ++mt) {
;           const float4 d4 = *(const float4*)(sDEC + mt * 16 + g * 4);
; #pragma unroll
;           for (int nt = 0; nt < 2; ++nt) {
;             sacc[mt][nt][0] *= d4.x;
;             sacc[mt][nt][1] *= d4.y;
;             sacc[mt][nt][2] *= d4.z;
;             sacc[mt][nt][3] *= d4.w;
;           }
; #pragma unroll
;           for (int kk = 0; kk < 2; ++kk) {
;             const bf16x8 kef = *(const bf16x8*)(sKET + (mt * 16 + fr) * 72 + kk * 32 + g * 8);
;             sacc[mt][0] = mfma16(kef, vf[0][kk], sacc[mt][0]);
;             sacc[mt][1] = mfma16(kef, vf[1][kk], sacc[mt][1]);
;           }
; #pragma unroll
;           for (int nt = 0; nt < 2; ++nt) {
;             uint2 v;
;             v.x = pack2(sacc[mt][nt][0], sacc[mt][nt][1]);
;             v.y = pack2(sacc[mt][nt][2], sacc[mt][nt][3]);
;             *(uint2*)(sST + (wave * 32 + nt * 16 + fr) * 136 + mt * 16 + g * 4) = v;
;           }
	v_mfma_f32_16x16x32_bf16 v[104:107], v[120:123], v[104:107], v[112:115]
	s_nop 2
	v_add_u32_e32 v112, 48, v166
	v_ashrrev_i32_e32 v113, 31, v112
	v_lshlrev_b64 v[112:113], 11, v[112:113]
	s_nop 1
	v_cvt_pk_bf16_f32 v104, v104, s0
	v_lshl_add_u64 v[112:113], v[162:163], 0, v[112:113]
	global_store_short v[112:113], v104, off
	v_add_u32_e32 v104, 49, v166
	v_cvt_pk_bf16_f32 v114, v105, s0
	v_ashrrev_i32_e32 v105, 31, v104
	v_lshlrev_b64 v[104:105], 11, v[104:105]
	v_lshl_add_u64 v[104:105], v[162:163], 0, v[104:105]
	v_mfma_f32_16x16x32_bf16 v[108:111], v[120:123], v[108:111], v[116:119]
	global_store_short v[104:105], v114, off
	v_add_u32_e32 v114, 50, v166
	v_ashrrev_i32_e32 v115, 31, v114
	v_lshlrev_b64 v[114:115], 11, v[114:115]
	v_cvt_pk_bf16_f32 v106, v106, s0
	v_lshl_add_u64 v[114:115], v[162:163], 0, v[114:115]
	global_store_short v[114:115], v106, off
	v_add_u32_e32 v106, 51, v166
	v_cvt_pk_bf16_f32 v108, v108, s0
	v_cvt_pk_bf16_f32 v116, v107, s0
	v_ashrrev_i32_e32 v107, 31, v106
	global_store_short v[112:113], v108, off offset:32
	v_cvt_pk_bf16_f32 v108, v109, s0
	v_lshlrev_b64 v[106:107], 11, v[106:107]
	global_store_short v[104:105], v108, off offset:32
	v_cvt_pk_bf16_f32 v104, v110, s0
	v_lshl_add_u64 v[106:107], v[162:163], 0, v[106:107]
	global_store_short v[114:115], v104, off offset:32
	v_cvt_pk_bf16_f32 v104, v111, s0
	global_store_short v[106:107], v116, off
	global_store_short v[106:107], v104, off offset:32
	ds_read_b128 v[104:107], v188
	v_mov_b32_e32 v166, v206
	s_waitcnt lgkmcnt(0)
	v_pk_mul_f32 v[26:27], v[26:27], v[106:107]
	v_pk_mul_f32 v[24:25], v[24:25], v[104:105]
	v_pk_mul_f32 v[30:31], v[30:31], v[106:107]
	v_pk_mul_f32 v[28:29], v[28:29], v[104:105]
	ds_read_b128 v[104:107], v204
	s_waitcnt lgkmcnt(0)
	v_mfma_f32_16x16x32_bf16 v[24:27], v[104:107], v[20:23], v[24:27]
	v_mfma_f32_16x16x32_bf16 v[28:31], v[104:107], v[16:19], v[28:31]
	ds_read_b128 v[104:107], v204 offset:64
	s_waitcnt lgkmcnt(0)
	v_mfma_f32_16x16x32_bf16 v[24:27], v[104:107], v[12:15], v[24:27]
	v_mfma_f32_16x16x32_bf16 v[28:31], v[104:107], v[8:11], v[28:31]
	s_nop 6
	v_cvt_pk_bf16_f32 v106, v24, v25
	v_cvt_pk_bf16_f32 v107, v26, v27
	v_add_u32_e32 v104, v180, v195
	ds_write_b64 v104, v[106:107]
	v_cvt_pk_bf16_f32 v106, v28, v29
	v_cvt_pk_bf16_f32 v107, v30, v31
	ds_write_b64 v104, v[106:107] offset:4352
	ds_read_b128 v[106:109], v188 offset:64
	s_waitcnt lgkmcnt(0)
	v_pk_mul_f32 v[34:35], v[34:35], v[108:109]
	v_pk_mul_f32 v[32:33], v[32:33], v[106:107]
	v_pk_mul_f32 v[38:39], v[38:39], v[108:109]
	v_pk_mul_f32 v[36:37], v[36:37], v[106:107]
	ds_read_b128 v[106:109], v204 offset:2304
	s_waitcnt lgkmcnt(0)
	v_mfma_f32_16x16x32_bf16 v[32:35], v[106:109], v[20:23], v[32:35]
	v_mfma_f32_16x16x32_bf16 v[36:39], v[106:109], v[16:19], v[36:39]
	ds_read_b128 v[106:109], v204 offset:2368
	s_waitcnt lgkmcnt(0)
	v_mfma_f32_16x16x32_bf16 v[32:35], v[106:109], v[12:15], v[32:35]
	v_mfma_f32_16x16x32_bf16 v[36:39], v[106:109], v[8:11], v[36:39]
	s_nop 6
	v_cvt_pk_bf16_f32 v106, v32, v33
	v_cvt_pk_bf16_f32 v107, v34, v35
	ds_write_b64 v104, v[106:107] offset:32
	v_cvt_pk_bf16_f32 v106, v36, v37
	v_cvt_pk_bf16_f32 v107, v38, v39
	ds_write_b64 v104, v[106:107] offset:4384
	ds_read_b128 v[106:109], v188 offset:128
	s_waitcnt lgkmcnt(0)
	v_pk_mul_f32 v[42:43], v[42:43], v[108:109]
	v_pk_mul_f32 v[40:41], v[40:41], v[106:107]
	v_pk_mul_f32 v[46:47], v[46:47], v[108:109]
	v_pk_mul_f32 v[44:45], v[44:45], v[106:107]
	ds_read_b128 v[106:109], v204 offset:4608
	s_waitcnt lgkmcnt(0)
	v_mfma_f32_16x16x32_bf16 v[40:43], v[106:109], v[20:23], v[40:43]
	v_mfma_f32_16x16x32_bf16 v[44:47], v[106:109], v[16:19], v[44:47]
	ds_read_b128 v[106:109], v204 offset:4672
	s_waitcnt lgkmcnt(0)
	v_mfma_f32_16x16x32_bf16 v[40:43], v[106:109], v[12:15], v[40:43]
	v_mfma_f32_16x16x32_bf16 v[44:47], v[106:109], v[8:11], v[44:47]
	s_nop 6
	v_cvt_pk_bf16_f32 v106, v40, v41
	v_cvt_pk_bf16_f32 v107, v42, v43
	ds_write_b64 v104, v[106:107] offset:64
	v_cvt_pk_bf16_f32 v106, v44, v45
	v_cvt_pk_bf16_f32 v107, v46, v47
	ds_write_b64 v104, v[106:107] offset:4416
	ds_read_b128 v[106:109], v188 offset:192
	s_waitcnt lgkmcnt(0)
	v_pk_mul_f32 v[50:51], v[50:51], v[108:109]
	v_pk_mul_f32 v[48:49], v[48:49], v[106:107]
	v_pk_mul_f32 v[54:55], v[54:55], v[108:109]
	v_pk_mul_f32 v[52:53], v[52:53], v[106:107]
	ds_read_b128 v[106:109], v204 offset:6912
	s_waitcnt lgkmcnt(0)
; DEVI f32x4 mfma16(bf16x8 a, bf16x8 b, f32x4 c) { return __builtin_amdgcn_mfma_f32_16x16x32_bf16(a, b, c, 0, 0, 0); }
; DEVI void gla_phase(int wv, const Params& p, char* smem) {
;     ...
; #pragma unroll
;         for (int mt = 0; mt < 8; ++mt) {
;           const float4 d4 = *(const float4*)(sDEC + mt * 16 + g * 4);
; #pragma unroll
;           for (int nt = 0; nt < 2; ++nt) {
;             sacc[mt][nt][0] *= d4.x;
;             sacc[mt][nt][1] *= d4.y;
;             sacc[mt][nt][2] *= d4.z;
;             sacc[mt][nt][3] *= d4.w;
;           }
; #pragma unroll
;           for (int kk = 0; kk < 2; ++kk) {
;             const bf16x8 kef = *(const bf16x8*)(sKET + (mt * 16 + fr) * 72 + kk * 32 + g * 8);
;             sacc[mt][0] = mfma16(kef, vf[0][kk], sacc[mt][0]);
;             sacc[mt][1] = mfma16(kef, vf[1][kk], sacc[mt][1]);
;           }
; #pragma unroll
;           for (int nt = 0; nt < 2; ++nt) {
;             uint2 v;
;             v.x = pack2(sacc[mt][nt][0], sacc[mt][nt][1]);
;             v.y = pack2(sacc[mt][nt][2], sacc[mt][nt][3]);
;             *(uint2*)(sST + (wave * 32 + nt * 16 + fr) * 136 + mt * 16 + g * 4) = v;
;           }
;         }
;       }
;       __syncthreads();
	v_mfma_f32_16x16x32_bf16 v[48:51], v[106:109], v[20:23], v[48:51]
	v_mfma_f32_16x16x32_bf16 v[52:55], v[106:109], v[16:19], v[52:55]
	ds_read_b128 v[106:109], v204 offset:6976
	s_waitcnt lgkmcnt(0)
	v_mfma_f32_16x16x32_bf16 v[48:51], v[106:109], v[12:15], v[48:51]
	v_mfma_f32_16x16x32_bf16 v[52:55], v[106:109], v[8:11], v[52:55]
	s_nop 6
	v_cvt_pk_bf16_f32 v106, v48, v49
	v_cvt_pk_bf16_f32 v107, v50, v51
	ds_write_b64 v104, v[106:107] offset:96
	v_cvt_pk_bf16_f32 v106, v52, v53
	v_cvt_pk_bf16_f32 v107, v54, v55
	ds_write_b64 v104, v[106:107] offset:4448
	ds_read_b128 v[106:109], v188 offset:256
	s_waitcnt lgkmcnt(0)
	v_pk_mul_f32 v[58:59], v[58:59], v[108:109]
	v_pk_mul_f32 v[56:57], v[56:57], v[106:107]
	v_pk_mul_f32 v[62:63], v[62:63], v[108:109]
	v_pk_mul_f32 v[60:61], v[60:61], v[106:107]
	ds_read_b128 v[106:109], v204 offset:9216
	s_waitcnt lgkmcnt(0)
	v_mfma_f32_16x16x32_bf16 v[56:59], v[106:109], v[20:23], v[56:59]
	v_mfma_f32_16x16x32_bf16 v[60:63], v[106:109], v[16:19], v[60:63]
	ds_read_b128 v[106:109], v204 offset:9280
	s_waitcnt lgkmcnt(0)
	v_mfma_f32_16x16x32_bf16 v[56:59], v[106:109], v[12:15], v[56:59]
	v_mfma_f32_16x16x32_bf16 v[60:63], v[106:109], v[8:11], v[60:63]
	s_nop 6
	v_cvt_pk_bf16_f32 v106, v56, v57
	v_cvt_pk_bf16_f32 v107, v58, v59
	ds_write_b64 v104, v[106:107] offset:128
	v_cvt_pk_bf16_f32 v106, v60, v61
	v_cvt_pk_bf16_f32 v107, v62, v63
	ds_write_b64 v104, v[106:107] offset:4480
	ds_read_b128 v[106:109], v188 offset:320
	s_waitcnt lgkmcnt(0)
	v_pk_mul_f32 v[66:67], v[66:67], v[108:109]
	v_pk_mul_f32 v[64:65], v[64:65], v[106:107]
	v_pk_mul_f32 v[70:71], v[70:71], v[108:109]
	v_pk_mul_f32 v[68:69], v[68:69], v[106:107]
	ds_read_b128 v[106:109], v204 offset:11520
	s_waitcnt lgkmcnt(0)
	v_mfma_f32_16x16x32_bf16 v[64:67], v[106:109], v[20:23], v[64:67]
	v_mfma_f32_16x16x32_bf16 v[68:71], v[106:109], v[16:19], v[68:71]
	ds_read_b128 v[106:109], v204 offset:11584
	s_waitcnt lgkmcnt(0)
	v_mfma_f32_16x16x32_bf16 v[64:67], v[106:109], v[12:15], v[64:67]
	v_mfma_f32_16x16x32_bf16 v[68:71], v[106:109], v[8:11], v[68:71]
	s_nop 6
	v_cvt_pk_bf16_f32 v106, v64, v65
	v_cvt_pk_bf16_f32 v107, v66, v67
	ds_write_b64 v104, v[106:107] offset:160
	v_cvt_pk_bf16_f32 v106, v68, v69
	v_cvt_pk_bf16_f32 v107, v70, v71
	ds_write_b64 v104, v[106:107] offset:4512
	ds_read_b128 v[106:109], v188 offset:384
	s_waitcnt lgkmcnt(0)
	v_pk_mul_f32 v[74:75], v[74:75], v[108:109]
	v_pk_mul_f32 v[72:73], v[72:73], v[106:107]
	v_pk_mul_f32 v[78:79], v[78:79], v[108:109]
	v_pk_mul_f32 v[76:77], v[76:77], v[106:107]
	ds_read_b128 v[106:109], v204 offset:13824
	s_waitcnt lgkmcnt(0)
	v_mfma_f32_16x16x32_bf16 v[72:75], v[106:109], v[20:23], v[72:75]
	v_mfma_f32_16x16x32_bf16 v[76:79], v[106:109], v[16:19], v[76:79]
	ds_read_b128 v[106:109], v204 offset:13888
	s_waitcnt lgkmcnt(0)
	v_mfma_f32_16x16x32_bf16 v[72:75], v[106:109], v[12:15], v[72:75]
	v_mfma_f32_16x16x32_bf16 v[76:79], v[106:109], v[8:11], v[76:79]
	s_nop 6
	v_cvt_pk_bf16_f32 v106, v72, v73
	v_cvt_pk_bf16_f32 v107, v74, v75
	ds_write_b64 v104, v[106:107] offset:192
	v_cvt_pk_bf16_f32 v106, v76, v77
	v_cvt_pk_bf16_f32 v107, v78, v79
	ds_write_b64 v104, v[106:107] offset:4544
	ds_read_b128 v[106:109], v188 offset:448
	s_waitcnt lgkmcnt(0)
	v_pk_mul_f32 v[82:83], v[82:83], v[108:109]
	v_pk_mul_f32 v[80:81], v[80:81], v[106:107]
	v_pk_mul_f32 v[86:87], v[86:87], v[108:109]
	v_pk_mul_f32 v[84:85], v[84:85], v[106:107]
	ds_read_b128 v[106:109], v204 offset:16128
	s_waitcnt lgkmcnt(0)
	v_mfma_f32_16x16x32_bf16 v[20:23], v[106:109], v[20:23], v[80:83]
	v_mfma_f32_16x16x32_bf16 v[16:19], v[106:109], v[16:19], v[84:87]
	s_nop 2
	ds_read_b128 v[84:87], v204 offset:16192
	s_waitcnt lgkmcnt(0)
	v_mfma_f32_16x16x32_bf16 v[80:83], v[84:87], v[12:15], v[20:23]
	v_mov_b64_e32 v[12:13], v[92:93]
	s_nop 1
	v_mov_b64_e32 v[20:21], v[88:89]
	v_mov_b64_e32 v[14:15], v[94:95]
	v_mfma_f32_16x16x32_bf16 v[84:87], v[84:87], v[8:11], v[16:19]
	s_nop 1
	v_cvt_pk_bf16_f32 v8, v80, v81
	v_cvt_pk_bf16_f32 v9, v82, v83
	ds_write_b64 v104, v[8:9] offset:224
	v_mov_b64_e32 v[16:17], v[96:97]
	v_mov_b64_e32 v[18:19], v[98:99]
	s_nop 0
	v_cvt_pk_bf16_f32 v8, v84, v85
	v_cvt_pk_bf16_f32 v9, v86, v87
	ds_write_b64 v104, v[8:9] offset:4576
	v_mov_b64_e32 v[8:9], v[100:101]
	v_mov_b64_e32 v[10:11], v[102:103]
	v_mov_b64_e32 v[22:23], v[90:91]
	s_waitcnt lgkmcnt(0)
	s_barrier
	s_cbranch_scc1 .LBB0_1316
	.p2align	6

; DEVI f32x4 ozero() { float z = 0.f; asm volatile("" : "+v"(z)); return f32x4{z, z, z, z}; }
; #define WAIT_V(n) asm volatile("s_waitcnt vmcnt(" #n ")" ::: "memory")
; #define BAR __builtin_amdgcn_s_barrier()
; template <int EPI> ...
;     ...
;   const int brow = m0, bcol = n0;
;   const int wid = __builtin_amdgcn_readfirstlane(tid >> 6), lane = tid & 63, wr = wid >> 2, wc = wid & 3, fr = lane & 15, fq = lane >> 4;
;   f32x4 acc[2][2][4][2];
;   {
;     const f32x4 zq = ozero();
; #pragma unroll
;     for (int a_ = 0; a_ < 2; ++a_)
; #pragma unroll
;       for (int b_ = 0; b_ < 2; ++b_)
; #pragma unroll
;         for (int m = 0; m < 4; ++m) { acc[a_][b_][m][0] = zq; acc[a_][b_][m][1] = zq; }
;   }
;   bf16x8 At[4][2], B0[2][2], B1[2][2];
;   const int nt = K / BK;
;     ...
;   if (first) {
;     WAIT_V(0);
;     ISSUE_PRO(brow, bcol);
;   }
;   if (wr == 1) BAR;
;   WAIT_V(10); BAR;
;   WAIT_V(6); BAR;
;   for (int t = 0; t < nt - 2; t += 2) {
.LBB0_1665:
	v_and_b32_e32 v133, 15, v132
	v_and_b32_e32 v1, 48, v132
	v_lshlrev_b32_e32 v2, 6, v133
	v_lshlrev_b32_e32 v4, 2, v132
	v_or_b32_e32 v3, v2, v1
	v_and_b32_e32 v4, 32, v4
	s_mov_b32 s18, 0x10000
	v_bitop3_b32 v5, v3, s18, v4 bitop3:0xde
	s_mov_b32 s18, 0x14000
	s_ashr_i32 s31, s30, 6
	v_bitop3_b32 v6, v3, s18, v4 bitop3:0xde
	s_mov_b32 s18, 0x18000
	s_and_b32 s9, s31, 3
	s_waitcnt vmcnt(10)
	s_barrier
	s_waitcnt vmcnt(6)
	v_bitop3_b32 v7, v3, s18, v4 bitop3:0xde
	s_mov_b32 s18, 0x1c000
	v_lshlrev_b32_e32 v8, 6, v132
	s_lshl_b32 s21, s9, 12
	v_bitop3_b32 v2, v2, v4, v1 bitop3:0x36
	s_lshl_b32 s34, s20, 6
	v_bitop3_b32 v3, v3, s18, v4 bitop3:0xde
	s_lshl_b32 s20, s20, 13
	v_and_b32_e32 v8, 0x3c0, v8
	v_bitop3_b32 v154, v8, v4, v1 bitop3:0x36
	s_or_b32 s35, s20, 0x800
	s_or_b32 s67, s20, 0x1000
	s_or_b32 s68, s20, 0x1800
	s_mov_b32 s69, -2
	s_mov_b64 s[18:19], 0
	v_add_u32_e32 v155, s21, v5
	v_add_u32_e32 v135, s20, v2
	v_add_u32_e32 v152, s21, v6
	v_add_u32_e32 v140, s21, v7
	v_add_u32_e32 v137, s21, v3
	v_mov_b32_e32 v1, v0
	v_mov_b32_e32 v2, v0
	v_mov_b32_e32 v3, v0
	v_mov_b32_e32 v4, v0
	v_mov_b32_e32 v5, v0
	v_mov_b32_e32 v6, v0
	v_mov_b32_e32 v7, v0
	v_mov_b32_e32 v8, v0
	v_mov_b32_e32 v9, v0
	v_mov_b32_e32 v10, v0
	v_mov_b32_e32 v11, v0
	v_mov_b32_e32 v12, v0
	v_mov_b32_e32 v13, v0
	v_mov_b32_e32 v14, v0
	v_mov_b32_e32 v15, v0
	v_mov_b32_e32 v16, v0
	v_mov_b32_e32 v17, v0
	v_mov_b32_e32 v18, v0
	v_mov_b32_e32 v19, v0
	v_mov_b32_e32 v20, v0
	v_mov_b32_e32 v21, v0
	v_mov_b32_e32 v22, v0
	v_mov_b32_e32 v23, v0
	v_mov_b32_e32 v24, v0
	v_mov_b32_e32 v25, v0
	v_mov_b32_e32 v26, v0
	v_mov_b32_e32 v27, v0
	v_mov_b32_e32 v28, v0
	v_mov_b32_e32 v29, v0
	v_mov_b32_e32 v30, v0
	v_mov_b32_e32 v31, v0
	v_mov_b32_e32 v32, v0
	v_mov_b32_e32 v33, v0
	v_mov_b32_e32 v34, v0
	v_mov_b32_e32 v35, v0
	v_mov_b32_e32 v36, v0
	v_mov_b32_e32 v37, v0
	v_mov_b32_e32 v38, v0
	v_mov_b32_e32 v39, v0
	v_mov_b32_e32 v40, v0
	v_mov_b32_e32 v41, v0
	v_mov_b32_e32 v42, v0
	v_mov_b32_e32 v43, v0
	v_mov_b32_e32 v44, v0
	v_mov_b32_e32 v45, v0
	v_mov_b32_e32 v46, v0
	v_mov_b32_e32 v47, v0
	v_mov_b32_e32 v48, v0
	v_mov_b32_e32 v49, v0
	v_mov_b32_e32 v50, v0
	v_mov_b32_e32 v51, v0
	v_mov_b32_e32 v52, v0
	v_mov_b32_e32 v53, v0
	v_mov_b32_e32 v54, v0
	v_mov_b32_e32 v55, v0
	v_mov_b32_e32 v56, v0
	v_mov_b32_e32 v57, v0
	v_mov_b32_e32 v58, v0
	v_mov_b32_e32 v59, v0
	v_mov_b32_e32 v60, v0
	v_mov_b32_e32 v61, v0
	v_mov_b32_e32 v62, v0
	v_mov_b32_e32 v63, v0
	v_mov_b32_e32 v64, v0
	v_mov_b32_e32 v65, v0
	v_mov_b32_e32 v66, v0
	v_mov_b32_e32 v67, v0
	v_mov_b32_e32 v68, v0
	v_mov_b32_e32 v69, v0
	v_mov_b32_e32 v70, v0
	v_mov_b32_e32 v71, v0
	v_mov_b32_e32 v72, v0
	v_mov_b32_e32 v73, v0
	v_mov_b32_e32 v74, v0
	v_mov_b32_e32 v75, v0
	v_mov_b32_e32 v76, v0
	v_mov_b32_e32 v77, v0
	v_mov_b32_e32 v78, v0
	v_mov_b32_e32 v79, v0
	v_mov_b32_e32 v80, v0
	v_mov_b32_e32 v81, v0
	v_mov_b32_e32 v82, v0
	v_mov_b32_e32 v83, v0
	v_mov_b32_e32 v84, v0
	v_mov_b32_e32 v85, v0
	v_mov_b32_e32 v86, v0
	v_mov_b32_e32 v87, v0
	v_mov_b32_e32 v88, v0
	v_mov_b32_e32 v89, v0
	v_mov_b32_e32 v90, v0
	v_mov_b32_e32 v91, v0
	v_mov_b32_e32 v92, v0
	v_mov_b32_e32 v93, v0
	v_mov_b32_e32 v94, v0
	v_mov_b32_e32 v95, v0
	v_mov_b32_e32 v96, v0
	v_mov_b32_e32 v97, v0
	v_mov_b32_e32 v98, v0
	v_mov_b32_e32 v99, v0
	v_mov_b32_e32 v100, v0
	v_mov_b32_e32 v101, v0
	v_mov_b32_e32 v102, v0
	v_mov_b32_e32 v103, v0
	v_mov_b32_e32 v104, v0
	v_mov_b32_e32 v105, v0
	v_mov_b32_e32 v106, v0
	v_mov_b32_e32 v107, v0
	v_mov_b32_e32 v108, v0
	v_mov_b32_e32 v109, v0
	v_mov_b32_e32 v110, v0
	v_mov_b32_e32 v111, v0
	v_mov_b32_e32 v112, v0
	v_mov_b32_e32 v113, v0
	v_mov_b32_e32 v114, v0
	v_mov_b32_e32 v115, v0
	v_mov_b32_e32 v116, v0
	v_mov_b32_e32 v117, v0
	v_mov_b32_e32 v118, v0
	v_mov_b32_e32 v119, v0
	v_mov_b32_e32 v120, v0
	v_mov_b32_e32 v121, v0
	v_mov_b32_e32 v122, v0
	v_mov_b32_e32 v123, v0
	v_mov_b32_e32 v124, v0
	v_mov_b32_e32 v125, v0
	v_mov_b32_e32 v126, v0
	v_mov_b32_e32 v127, v0
	s_barrier
	v_lshlrev_b32_e32 v253, 1, v128
	v_lshlrev_b32_e32 v252, 1, v130
	v_readfirstlane_b32 s32, v129
	.p2align	6

; DEVI f32x4 ozero() { float z = 0.f; asm volatile("" : "+v"(z)); return f32x4{z, z, z, z}; }
; #define WAIT_V(n) asm volatile("s_waitcnt vmcnt(" #n ")" ::: "memory")
; #define BAR __builtin_amdgcn_s_barrier()
; template <int EPI> ...
;     ...
;   const int brow = m0, bcol = n0;
;   const int wid = __builtin_amdgcn_readfirstlane(tid >> 6), lane = tid & 63, wr = wid >> 2, wc = wid & 3, fr = lane & 15, fq = lane >> 4;
;   f32x4 acc[2][2][4][2];
;   {
;     const f32x4 zq = ozero();
; #pragma unroll
;     for (int a_ = 0; a_ < 2; ++a_)
; #pragma unroll
;       for (int b_ = 0; b_ < 2; ++b_)
; #pragma unroll
;         for (int m = 0; m < 4; ++m) { acc[a_][b_][m][0] = zq; acc[a_][b_][m][1] = zq; }
;   }
;   bf16x8 At[4][2], B0[2][2], B1[2][2];
;   const int nt = K / BK;
;     ...
;   if (first) {
;     WAIT_V(0);
;     ISSUE_PRO(brow, bcol);
;   }
;   if (wr == 1) BAR;
;   WAIT_V(10); BAR;
;   WAIT_V(6); BAR;
;   for (int t = 0; t < nt - 2; t += 2) {
.LBB0_1753:
	v_and_b32_e32 v132, 15, v134
	v_and_b32_e32 v1, 48, v134
	v_lshlrev_b32_e32 v2, 6, v132
	v_lshlrev_b32_e32 v4, 2, v134
	v_or_b32_e32 v3, v2, v1
	v_and_b32_e32 v4, 32, v4
	s_mov_b32 s16, 0x10000
	v_bitop3_b32 v5, v3, s16, v4 bitop3:0xde
	s_mov_b32 s16, 0x14000
	s_ashr_i32 s9, s62, 6
	v_bitop3_b32 v6, v3, s16, v4 bitop3:0xde
	s_mov_b32 s16, 0x18000
	s_and_b32 s63, s9, 3
	s_waitcnt vmcnt(10)
	s_barrier
	s_waitcnt vmcnt(6)
	v_bitop3_b32 v7, v3, s16, v4 bitop3:0xde
	s_mov_b32 s16, 0x1c000
	v_lshlrev_b32_e32 v8, 6, v134
	s_lshl_b32 s19, s63, 12
	v_bitop3_b32 v2, v2, v4, v1 bitop3:0x36
	s_lshl_b32 s64, s18, 6
	v_bitop3_b32 v3, v3, s16, v4 bitop3:0xde
	s_lshl_b32 s18, s18, 13
	v_and_b32_e32 v8, 0x3c0, v8
	v_bitop3_b32 v154, v8, v4, v1 bitop3:0x36
	s_or_b32 s65, s18, 0x800
	s_or_b32 s66, s18, 0x1000
	s_or_b32 s67, s18, 0x1800
	s_mov_b32 s68, -2
	s_mov_b64 s[16:17], 0
	v_add_u32_e32 v155, s19, v5
	v_add_u32_e32 v135, s18, v2
	v_add_u32_e32 v152, s19, v6
	v_add_u32_e32 v140, s19, v7
	v_add_u32_e32 v137, s19, v3
	v_mov_b32_e32 v1, v0
	v_mov_b32_e32 v2, v0
	v_mov_b32_e32 v3, v0
	v_mov_b32_e32 v4, v0
	v_mov_b32_e32 v5, v0
	v_mov_b32_e32 v6, v0
	v_mov_b32_e32 v7, v0
	v_mov_b32_e32 v8, v0
	v_mov_b32_e32 v9, v0
	v_mov_b32_e32 v10, v0
	v_mov_b32_e32 v11, v0
	v_mov_b32_e32 v12, v0
	v_mov_b32_e32 v13, v0
	v_mov_b32_e32 v14, v0
	v_mov_b32_e32 v15, v0
	v_mov_b32_e32 v16, v0
	v_mov_b32_e32 v17, v0
	v_mov_b32_e32 v18, v0
	v_mov_b32_e32 v19, v0
	v_mov_b32_e32 v20, v0
	v_mov_b32_e32 v21, v0
	v_mov_b32_e32 v22, v0
	v_mov_b32_e32 v23, v0
	v_mov_b32_e32 v24, v0
	v_mov_b32_e32 v25, v0
	v_mov_b32_e32 v26, v0
	v_mov_b32_e32 v27, v0
	v_mov_b32_e32 v28, v0
	v_mov_b32_e32 v29, v0
	v_mov_b32_e32 v30, v0
	v_mov_b32_e32 v31, v0
	v_mov_b32_e32 v32, v0
	v_mov_b32_e32 v33, v0
	v_mov_b32_e32 v34, v0
	v_mov_b32_e32 v35, v0
	v_mov_b32_e32 v36, v0
	v_mov_b32_e32 v37, v0
	v_mov_b32_e32 v38, v0
	v_mov_b32_e32 v39, v0
	v_mov_b32_e32 v40, v0
	v_mov_b32_e32 v41, v0
	v_mov_b32_e32 v42, v0
	v_mov_b32_e32 v43, v0
	v_mov_b32_e32 v44, v0
	v_mov_b32_e32 v45, v0
	v_mov_b32_e32 v46, v0
	v_mov_b32_e32 v47, v0
	v_mov_b32_e32 v48, v0
	v_mov_b32_e32 v49, v0
	v_mov_b32_e32 v50, v0
	v_mov_b32_e32 v51, v0
	v_mov_b32_e32 v52, v0
	v_mov_b32_e32 v53, v0
	v_mov_b32_e32 v54, v0
	v_mov_b32_e32 v55, v0
	v_mov_b32_e32 v56, v0
	v_mov_b32_e32 v57, v0
	v_mov_b32_e32 v58, v0
	v_mov_b32_e32 v59, v0
	v_mov_b32_e32 v60, v0
	v_mov_b32_e32 v61, v0
	v_mov_b32_e32 v62, v0
	v_mov_b32_e32 v63, v0
	v_mov_b32_e32 v64, v0
	v_mov_b32_e32 v65, v0
	v_mov_b32_e32 v66, v0
	v_mov_b32_e32 v67, v0
	v_mov_b32_e32 v68, v0
	v_mov_b32_e32 v69, v0
	v_mov_b32_e32 v70, v0
	v_mov_b32_e32 v71, v0
	v_mov_b32_e32 v72, v0
	v_mov_b32_e32 v73, v0
	v_mov_b32_e32 v74, v0
	v_mov_b32_e32 v75, v0
	v_mov_b32_e32 v76, v0
	v_mov_b32_e32 v77, v0
	v_mov_b32_e32 v78, v0
	v_mov_b32_e32 v79, v0
	v_mov_b32_e32 v80, v0
	v_mov_b32_e32 v81, v0
	v_mov_b32_e32 v82, v0
	v_mov_b32_e32 v83, v0
	v_mov_b32_e32 v84, v0
	v_mov_b32_e32 v85, v0
	v_mov_b32_e32 v86, v0
	v_mov_b32_e32 v87, v0
	v_mov_b32_e32 v88, v0
	v_mov_b32_e32 v89, v0
	v_mov_b32_e32 v90, v0
	v_mov_b32_e32 v91, v0
	v_mov_b32_e32 v92, v0
	v_mov_b32_e32 v93, v0
	v_mov_b32_e32 v94, v0
	v_mov_b32_e32 v95, v0
	v_mov_b32_e32 v96, v0
	v_mov_b32_e32 v97, v0
	v_mov_b32_e32 v98, v0
	v_mov_b32_e32 v99, v0
	v_mov_b32_e32 v100, v0
	v_mov_b32_e32 v101, v0
	v_mov_b32_e32 v102, v0
	v_mov_b32_e32 v103, v0
	v_mov_b32_e32 v104, v0
	v_mov_b32_e32 v105, v0
	v_mov_b32_e32 v106, v0
	v_mov_b32_e32 v107, v0
	v_mov_b32_e32 v108, v0
	v_mov_b32_e32 v109, v0
	v_mov_b32_e32 v110, v0
	v_mov_b32_e32 v111, v0
	v_mov_b32_e32 v112, v0
	v_mov_b32_e32 v113, v0
	v_mov_b32_e32 v114, v0
	v_mov_b32_e32 v115, v0
	v_mov_b32_e32 v116, v0
	v_mov_b32_e32 v117, v0
	v_mov_b32_e32 v118, v0
	v_mov_b32_e32 v119, v0
	v_mov_b32_e32 v120, v0
	v_mov_b32_e32 v121, v0
	v_mov_b32_e32 v122, v0
	v_mov_b32_e32 v123, v0
	v_mov_b32_e32 v124, v0
	v_mov_b32_e32 v125, v0
	v_mov_b32_e32 v126, v0
	v_mov_b32_e32 v127, v0
	s_barrier
	v_lshlrev_b32_e32 v253, 1, v128
	v_lshlrev_b32_e32 v252, 1, v130
	v_readfirstlane_b32 s32, v133
	.p2align	6

; DEVI f32x4 ozero() { float z = 0.f; asm volatile("" : "+v"(z)); return f32x4{z, z, z, z}; }
; #define WAIT_V(n) asm volatile("s_waitcnt vmcnt(" #n ")" ::: "memory")
; #define BAR __builtin_amdgcn_s_barrier()
; template <int EPI> ...
;     ...
;   const int brow = m0, bcol = n0;
;   const int wid = __builtin_amdgcn_readfirstlane(tid >> 6), lane = tid & 63, wr = wid >> 2, wc = wid & 3, fr = lane & 15, fq = lane >> 4;
;   f32x4 acc[2][2][4][2];
;   {
;     const f32x4 zq = ozero();
; #pragma unroll
;     for (int a_ = 0; a_ < 2; ++a_)
; #pragma unroll
;       for (int b_ = 0; b_ < 2; ++b_)
; #pragma unroll
;         for (int m = 0; m < 4; ++m) { acc[a_][b_][m][0] = zq; acc[a_][b_][m][1] = zq; }
;   }
;   bf16x8 At[4][2], B0[2][2], B1[2][2];
;   const int nt = K / BK;
;     ...
;   if (first) {
;     WAIT_V(0);
;     ISSUE_PRO(brow, bcol);
;   }
;   if (wr == 1) BAR;
;   WAIT_V(10); BAR;
;   WAIT_V(6); BAR;
;   for (int t = 0; t < nt - 2; t += 2) {
.LBB0_1778:
	v_and_b32_e32 v133, 15, v132
	v_and_b32_e32 v1, 48, v132
	v_lshlrev_b32_e32 v2, 6, v133
	v_lshlrev_b32_e32 v4, 2, v132
	v_or_b32_e32 v3, v2, v1
	v_and_b32_e32 v4, 32, v4
	s_mov_b32 s16, 0x10000
	v_bitop3_b32 v5, v3, s16, v4 bitop3:0xde
	s_mov_b32 s16, 0x14000
	s_ashr_i32 s34, s30, 6
	v_bitop3_b32 v6, v3, s16, v4 bitop3:0xde
	s_mov_b32 s16, 0x18000
	s_and_b32 s35, s34, 3
	s_waitcnt vmcnt(10)
	s_barrier
	s_waitcnt vmcnt(6)
	v_bitop3_b32 v7, v3, s16, v4 bitop3:0xde
	s_mov_b32 s16, 0x1c000
	v_lshlrev_b32_e32 v8, 6, v132
	s_lshl_b32 s19, s35, 12
	v_bitop3_b32 v2, v2, v4, v1 bitop3:0x36
	s_lshl_b32 s62, s18, 6
	v_bitop3_b32 v3, v3, s16, v4 bitop3:0xde
	s_lshl_b32 s18, s18, 13
	v_and_b32_e32 v8, 0x3c0, v8
	s_ashr_i32 s31, s23, 31
	v_bitop3_b32 v154, v8, v4, v1 bitop3:0x36
	s_or_b32 s63, s18, 0x800
	s_or_b32 s68, s18, 0x1000
	s_or_b32 s69, s18, 0x1800
	s_mov_b32 s70, -2
	s_mov_b64 s[16:17], 0
	v_add_u32_e32 v155, s19, v5
	v_add_u32_e32 v135, s18, v2
	v_add_u32_e32 v152, s19, v6
	v_add_u32_e32 v140, s19, v7
	v_add_u32_e32 v137, s19, v3
	v_mov_b32_e32 v1, v0
	v_mov_b32_e32 v2, v0
	v_mov_b32_e32 v3, v0
	v_mov_b32_e32 v4, v0
	v_mov_b32_e32 v5, v0
	v_mov_b32_e32 v6, v0
	v_mov_b32_e32 v7, v0
	v_mov_b32_e32 v8, v0
	v_mov_b32_e32 v9, v0
	v_mov_b32_e32 v10, v0
	v_mov_b32_e32 v11, v0
	v_mov_b32_e32 v12, v0
	v_mov_b32_e32 v13, v0
	v_mov_b32_e32 v14, v0
	v_mov_b32_e32 v15, v0
	v_mov_b32_e32 v16, v0
	v_mov_b32_e32 v17, v0
	v_mov_b32_e32 v18, v0
	v_mov_b32_e32 v19, v0
	v_mov_b32_e32 v20, v0
	v_mov_b32_e32 v21, v0
	v_mov_b32_e32 v22, v0
	v_mov_b32_e32 v23, v0
	v_mov_b32_e32 v24, v0
	v_mov_b32_e32 v25, v0
	v_mov_b32_e32 v26, v0
	v_mov_b32_e32 v27, v0
	v_mov_b32_e32 v28, v0
	v_mov_b32_e32 v29, v0
	v_mov_b32_e32 v30, v0
	v_mov_b32_e32 v31, v0
	v_mov_b32_e32 v32, v0
	v_mov_b32_e32 v33, v0
	v_mov_b32_e32 v34, v0
	v_mov_b32_e32 v35, v0
	v_mov_b32_e32 v36, v0
	v_mov_b32_e32 v37, v0
	v_mov_b32_e32 v38, v0
	v_mov_b32_e32 v39, v0
	v_mov_b32_e32 v40, v0
	v_mov_b32_e32 v41, v0
	v_mov_b32_e32 v42, v0
	v_mov_b32_e32 v43, v0
	v_mov_b32_e32 v44, v0
	v_mov_b32_e32 v45, v0
	v_mov_b32_e32 v46, v0
	v_mov_b32_e32 v47, v0
	v_mov_b32_e32 v48, v0
	v_mov_b32_e32 v49, v0
	v_mov_b32_e32 v50, v0
	v_mov_b32_e32 v51, v0
	v_mov_b32_e32 v52, v0
	v_mov_b32_e32 v53, v0
	v_mov_b32_e32 v54, v0
	v_mov_b32_e32 v55, v0
	v_mov_b32_e32 v56, v0
	v_mov_b32_e32 v57, v0
	v_mov_b32_e32 v58, v0
	v_mov_b32_e32 v59, v0
	v_mov_b32_e32 v60, v0
	v_mov_b32_e32 v61, v0
	v_mov_b32_e32 v62, v0
	v_mov_b32_e32 v63, v0
	v_mov_b32_e32 v64, v0
	v_mov_b32_e32 v65, v0
	v_mov_b32_e32 v66, v0
	v_mov_b32_e32 v67, v0
	v_mov_b32_e32 v68, v0
	v_mov_b32_e32 v69, v0
	v_mov_b32_e32 v70, v0
	v_mov_b32_e32 v71, v0
	v_mov_b32_e32 v72, v0
	v_mov_b32_e32 v73, v0
	v_mov_b32_e32 v74, v0
	v_mov_b32_e32 v75, v0
	v_mov_b32_e32 v76, v0
	v_mov_b32_e32 v77, v0
	v_mov_b32_e32 v78, v0
	v_mov_b32_e32 v79, v0
	v_mov_b32_e32 v80, v0
	v_mov_b32_e32 v81, v0
	v_mov_b32_e32 v82, v0
	v_mov_b32_e32 v83, v0
	v_mov_b32_e32 v84, v0
	v_mov_b32_e32 v85, v0
	v_mov_b32_e32 v86, v0
	v_mov_b32_e32 v87, v0
	v_mov_b32_e32 v88, v0
	v_mov_b32_e32 v89, v0
	v_mov_b32_e32 v90, v0
	v_mov_b32_e32 v91, v0
	v_mov_b32_e32 v92, v0
	v_mov_b32_e32 v93, v0
	v_mov_b32_e32 v94, v0
	v_mov_b32_e32 v95, v0
	v_mov_b32_e32 v96, v0
	v_mov_b32_e32 v97, v0
	v_mov_b32_e32 v98, v0
	v_mov_b32_e32 v99, v0
	v_mov_b32_e32 v100, v0
	v_mov_b32_e32 v101, v0
	v_mov_b32_e32 v102, v0
	v_mov_b32_e32 v103, v0
	v_mov_b32_e32 v104, v0
	v_mov_b32_e32 v105, v0
	v_mov_b32_e32 v106, v0
	v_mov_b32_e32 v107, v0
	v_mov_b32_e32 v108, v0
	v_mov_b32_e32 v109, v0
	v_mov_b32_e32 v110, v0
	v_mov_b32_e32 v111, v0
	v_mov_b32_e32 v112, v0
	v_mov_b32_e32 v113, v0
	v_mov_b32_e32 v114, v0
	v_mov_b32_e32 v115, v0
	v_mov_b32_e32 v116, v0
	v_mov_b32_e32 v117, v0
	v_mov_b32_e32 v118, v0
	v_mov_b32_e32 v119, v0
	v_mov_b32_e32 v120, v0
	v_mov_b32_e32 v121, v0
	v_mov_b32_e32 v122, v0
	v_mov_b32_e32 v123, v0
	v_mov_b32_e32 v124, v0
	v_mov_b32_e32 v125, v0
	v_mov_b32_e32 v126, v0
	v_mov_b32_e32 v127, v0
	s_barrier
	v_lshlrev_b32_e32 v253, 1, v128
	v_lshlrev_b32_e32 v252, 1, v130
	v_readfirstlane_b32 s32, v129
	.p2align	6

; DEVI f32x4 ozero() { float z = 0.f; asm volatile("" : "+v"(z)); return f32x4{z, z, z, z}; }
; #define WAIT_V(n) asm volatile("s_waitcnt vmcnt(" #n ")" ::: "memory")
; #define BAR __builtin_amdgcn_s_barrier()
; template <int EPI> ...
;     ...
;   const int brow = m0, bcol = n0;
;   const int wid = __builtin_amdgcn_readfirstlane(tid >> 6), lane = tid & 63, wr = wid >> 2, wc = wid & 3, fr = lane & 15, fq = lane >> 4;
;   f32x4 acc[2][2][4][2];
;   {
;     const f32x4 zq = ozero();
; #pragma unroll
;     for (int a_ = 0; a_ < 2; ++a_)
; #pragma unroll
;       for (int b_ = 0; b_ < 2; ++b_)
; #pragma unroll
;         for (int m = 0; m < 4; ++m) { acc[a_][b_][m][0] = zq; acc[a_][b_][m][1] = zq; }
;   }
;   bf16x8 At[4][2], B0[2][2], B1[2][2];
;   const int nt = K / BK;
;     ...
;   if (first) {
;     WAIT_V(0);
;     ISSUE_PRO(brow, bcol);
;   }
;   if (wr == 1) BAR;
;   WAIT_V(10); BAR;
;   WAIT_V(6); BAR;
.LBB0_1882:
	v_and_b32_e32 v143, 15, v132
	v_and_b32_e32 v1, 48, v132
	v_lshlrev_b32_e32 v2, 6, v143
	v_lshlrev_b32_e32 v4, 2, v132
	v_or_b32_e32 v3, v2, v1
	v_and_b32_e32 v4, 32, v4
	s_mov_b32 s30, 0x10000
	v_bitop3_b32 v5, v3, s30, v4 bitop3:0xde
	s_mov_b32 s30, 0x14000
	s_ashr_i32 s5, s64, 6
	v_bitop3_b32 v6, v3, s30, v4 bitop3:0xde
	s_mov_b32 s30, 0x18000
	s_and_b32 s65, s5, 3
	s_waitcnt vmcnt(10)
	s_barrier
	s_waitcnt vmcnt(6)
	v_bitop3_b32 v7, v3, s30, v4 bitop3:0xde
	s_mov_b32 s30, 0x1c000
	v_lshlrev_b32_e32 v8, 6, v132
	s_lshl_b32 s35, s65, 12
	v_bitop3_b32 v2, v2, v4, v1 bitop3:0x36
	s_lshl_b32 s66, s34, 6
	v_bitop3_b32 v3, v3, s30, v4 bitop3:0xde
	s_lshl_b32 s34, s34, 13
	v_and_b32_e32 v8, 0x3c0, v8
	v_bitop3_b32 v154, v8, v4, v1 bitop3:0x36
	s_or_b32 s67, s34, 0x800
	s_or_b32 s68, s34, 0x1000
	s_or_b32 s69, s34, 0x1800
	s_mov_b32 s70, -2
	s_mov_b64 s[30:31], 0
	v_add_u32_e32 v155, s35, v5
	v_add_u32_e32 v134, s34, v2
	v_add_u32_e32 v152, s35, v6
	v_add_u32_e32 v139, s35, v7
	v_add_u32_e32 v136, s35, v3
	v_mov_b32_e32 v1, v0
	v_mov_b32_e32 v2, v0
	v_mov_b32_e32 v3, v0
	v_mov_b32_e32 v4, v0
	v_mov_b32_e32 v5, v0
	v_mov_b32_e32 v6, v0
	v_mov_b32_e32 v7, v0
	v_mov_b32_e32 v8, v0
	v_mov_b32_e32 v9, v0
	v_mov_b32_e32 v10, v0
	v_mov_b32_e32 v11, v0
	v_mov_b32_e32 v12, v0
	v_mov_b32_e32 v13, v0
	v_mov_b32_e32 v14, v0
	v_mov_b32_e32 v15, v0
	v_mov_b32_e32 v16, v0
	v_mov_b32_e32 v17, v0
	v_mov_b32_e32 v18, v0
	v_mov_b32_e32 v19, v0
	v_mov_b32_e32 v20, v0
	v_mov_b32_e32 v21, v0
	v_mov_b32_e32 v22, v0
	v_mov_b32_e32 v23, v0
	v_mov_b32_e32 v24, v0
	v_mov_b32_e32 v25, v0
	v_mov_b32_e32 v26, v0
	v_mov_b32_e32 v27, v0
	v_mov_b32_e32 v28, v0
	v_mov_b32_e32 v29, v0
	v_mov_b32_e32 v30, v0
	v_mov_b32_e32 v31, v0
	v_mov_b32_e32 v32, v0
	v_mov_b32_e32 v33, v0
	v_mov_b32_e32 v34, v0
	v_mov_b32_e32 v35, v0
	v_mov_b32_e32 v36, v0
	v_mov_b32_e32 v37, v0
	v_mov_b32_e32 v38, v0
	v_mov_b32_e32 v39, v0
	v_mov_b32_e32 v40, v0
	v_mov_b32_e32 v41, v0
	v_mov_b32_e32 v42, v0
	v_mov_b32_e32 v43, v0
	v_mov_b32_e32 v44, v0
	v_mov_b32_e32 v45, v0
	v_mov_b32_e32 v46, v0
	v_mov_b32_e32 v47, v0
	v_mov_b32_e32 v48, v0
	v_mov_b32_e32 v49, v0
	v_mov_b32_e32 v50, v0
	v_mov_b32_e32 v51, v0
	v_mov_b32_e32 v52, v0
	v_mov_b32_e32 v53, v0
	v_mov_b32_e32 v54, v0
	v_mov_b32_e32 v55, v0
	v_mov_b32_e32 v56, v0
	v_mov_b32_e32 v57, v0
	v_mov_b32_e32 v58, v0
	v_mov_b32_e32 v59, v0
	v_mov_b32_e32 v60, v0
	v_mov_b32_e32 v61, v0
	v_mov_b32_e32 v62, v0
	v_mov_b32_e32 v63, v0
	v_mov_b32_e32 v64, v0
	v_mov_b32_e32 v65, v0
	v_mov_b32_e32 v66, v0
	v_mov_b32_e32 v67, v0
	v_mov_b32_e32 v68, v0
	v_mov_b32_e32 v69, v0
	v_mov_b32_e32 v70, v0
	v_mov_b32_e32 v71, v0
	v_mov_b32_e32 v72, v0
	v_mov_b32_e32 v73, v0
	v_mov_b32_e32 v74, v0
	v_mov_b32_e32 v75, v0
	v_mov_b32_e32 v76, v0
	v_mov_b32_e32 v77, v0
	v_mov_b32_e32 v78, v0
	v_mov_b32_e32 v79, v0
	v_mov_b32_e32 v80, v0
	v_mov_b32_e32 v81, v0
	v_mov_b32_e32 v82, v0
	v_mov_b32_e32 v83, v0
	v_mov_b32_e32 v84, v0
	v_mov_b32_e32 v85, v0
	v_mov_b32_e32 v86, v0
	v_mov_b32_e32 v87, v0
	v_mov_b32_e32 v88, v0
	v_mov_b32_e32 v89, v0
	v_mov_b32_e32 v90, v0
	v_mov_b32_e32 v91, v0
	v_mov_b32_e32 v92, v0
	v_mov_b32_e32 v93, v0
	v_mov_b32_e32 v94, v0
	v_mov_b32_e32 v95, v0
	v_mov_b32_e32 v96, v0
	v_mov_b32_e32 v97, v0
	v_mov_b32_e32 v98, v0
	v_mov_b32_e32 v99, v0
	v_mov_b32_e32 v100, v0
	v_mov_b32_e32 v101, v0
	v_mov_b32_e32 v102, v0
	v_mov_b32_e32 v103, v0
	v_mov_b32_e32 v104, v0
	v_mov_b32_e32 v105, v0
	v_mov_b32_e32 v106, v0
	v_mov_b32_e32 v107, v0
	v_mov_b32_e32 v108, v0
	v_mov_b32_e32 v109, v0
	v_mov_b32_e32 v110, v0
	v_mov_b32_e32 v111, v0
	v_mov_b32_e32 v112, v0
	v_mov_b32_e32 v113, v0
	v_mov_b32_e32 v114, v0
	v_mov_b32_e32 v115, v0
	v_mov_b32_e32 v116, v0
	v_mov_b32_e32 v117, v0
	v_mov_b32_e32 v118, v0
	v_mov_b32_e32 v119, v0
	v_mov_b32_e32 v120, v0
	v_mov_b32_e32 v121, v0
	v_mov_b32_e32 v122, v0
	v_mov_b32_e32 v123, v0
	v_mov_b32_e32 v124, v0
	v_mov_b32_e32 v125, v0
	v_mov_b32_e32 v126, v0
	v_mov_b32_e32 v127, v0
	s_barrier
	v_lshlrev_b32_e32 v253, 1, v128
	v_lshlrev_b32_e32 v252, 1, v130
	v_readfirstlane_b32 s32, v129
	.p2align	6
